# attention loops: ds_read->wait->mfma chains pipelined 3-4 reads deep with spare VGPRs; FoX bias-table reads issued together into the accumulator registers with in-place subtract
# speedup vs baseline: 1.0158x; 1.0066x over previous
.LBB0_198:
	s_cmp_gt_i32 s16, 2
	s_mov_b64 s[4:5], -1
	s_cbranch_scc0 .LBB0_309
	s_lshl_b32 s23, s28, 2
	s_lshl_b32 s14, s28, 8
	s_or_b32 s30, s23, 3
	s_mul_i32 s5, s27, 0x1800000
	v_readlane_b32 s6, v255, 11
	s_mul_hi_i32 s4, s27, 0x1800000
	v_readlane_b32 s7, v255, 12
	s_add_u32 s6, s6, s5
	s_addc_u32 s7, s7, s4
	s_lshl_b32 s4, s29, 3
	s_sub_i32 s4, 0xffffffd8, s4
	v_cvt_f32_i32_e32 v0, s4
	s_mov_b32 s8, 0x41400000
	v_mov_b32_e32 v198, v241
	v_mov_b32_e32 v11, v241
	v_div_scale_f32 v1, s[4:5], s8, s8, v0
	v_rcp_f32_e32 v2, v1
	s_mov_b32 s4, 0xc2fc0000
	v_fma_f32 v3, -v1, v2, 1.0
	v_fmac_f32_e32 v2, v3, v2
	v_div_scale_f32 v3, vcc, v0, s8, v0
	v_mul_f32_e32 v4, v3, v2
	v_fma_f32 v5, -v1, v4, v3
	v_fmac_f32_e32 v4, v5, v2
	v_fma_f32 v1, -v1, v4, v3
	v_div_fmas_f32 v1, v1, v2, v4
	v_div_fixup_f32 v0, v1, s8, v0
	v_cmp_gt_f32_e32 vcc, s4, v0
	s_and_b64 s[4:5], vcc, exec
	s_cselect_b32 s4, 0xffffffc0, 0
	v_cndmask_b32_e32 v1, 0, v238, vcc
	v_add_f32_e32 v0, v0, v1
	v_exp_f32_e32 v0, v0
	v_and_b32_e32 v14, 31, v11
	v_bfe_u32 v8, v11, 5, 1
	s_movk_i32 s8, 0x3000
	v_ldexp_f32 v0, v0, s4
	s_lshl_b32 s4, s29, 7
	s_add_u32 s4, s6, s4
	s_addc_u32 s5, s7, 0
	s_add_u32 s6, s4, 0x2400
	s_addc_u32 s7, s5, 0
	s_add_u32 s90, s4, 0x2800
	s_addc_u32 s91, s5, 0
	s_add_u32 s92, s4, 0x2c00
	s_addc_u32 s93, s5, 0
	v_readfirstlane_b32 s5, v11
	s_ashr_i32 s4, s5, 6
	s_lshl_b32 s31, s4, 5
	s_add_i32 s31, s31, s14
	v_mul_f32_e32 v192, 0x3fb8aa3b, v0
	v_or_b32_e32 v199, s31, v14
	v_mov_b64_e32 v[0:1], s[6:7]
	v_mad_i64_i32 v[0:1], s[6:7], v199, s8, v[0:1]
	v_lshlrev_b32_e32 v128, 4, v8
	v_lshl_add_u64 v[0:1], v[0:1], 0, v[128:129]
	global_load_dwordx4 v[2:5], v[0:1], off
	global_load_dwordx4 v[16:19], v[0:1], off offset:32
	global_load_dwordx4 v[20:23], v[0:1], off offset:64
	global_load_dwordx4 v[24:27], v[0:1], off offset:96
	s_mov_b32 s6, 0x3e38aa3b
	v_and_b32_e32 v10, 63, v11
	s_ashr_i32 s26, s5, 7
	v_lshlrev_b32_e32 v200, 2, v8
	v_readfirstlane_b32 s15, v198
	v_xor_b32_e32 v203, 0x80000000, v192
	s_waitcnt vmcnt(3)
	v_and_b32_e32 v7, 0xffff0000, v2
	v_lshlrev_b32_e32 v6, 16, v2
	v_pk_mul_f32 v[6:7], v[6:7], s[6:7] op_sel_hi:[1,0]
	s_nop 0
	v_cvt_pk_bf16_f32 v144, v6, v7
	v_and_b32_e32 v7, 0xffff0000, v3
	v_lshlrev_b32_e32 v6, 16, v3
	v_pk_mul_f32 v[2:3], v[6:7], s[6:7] op_sel_hi:[1,0]
	s_nop 0
	v_cvt_pk_bf16_f32 v145, v2, v3
	v_and_b32_e32 v3, 0xffff0000, v4
	v_lshlrev_b32_e32 v2, 16, v4
	v_pk_mul_f32 v[2:3], v[2:3], s[6:7] op_sel_hi:[1,0]
	s_nop 0
	v_cvt_pk_bf16_f32 v146, v2, v3
	v_and_b32_e32 v3, 0xffff0000, v5
	v_lshlrev_b32_e32 v2, 16, v5
	v_pk_mul_f32 v[2:3], v[2:3], s[6:7] op_sel_hi:[1,0]
	s_nop 0
	v_cvt_pk_bf16_f32 v147, v2, v3
	s_waitcnt vmcnt(2)
	v_and_b32_e32 v7, 0xffff0000, v16
	v_lshlrev_b32_e32 v6, 16, v16
	v_pk_mul_f32 v[6:7], v[6:7], s[6:7] op_sel_hi:[1,0]
	s_nop 0
	v_cvt_pk_bf16_f32 v148, v6, v7
	v_and_b32_e32 v7, 0xffff0000, v17
	v_lshlrev_b32_e32 v6, 16, v17
	v_pk_mul_f32 v[2:3], v[6:7], s[6:7] op_sel_hi:[1,0]
	s_nop 0
	v_cvt_pk_bf16_f32 v149, v2, v3
	v_and_b32_e32 v3, 0xffff0000, v18
	v_lshlrev_b32_e32 v2, 16, v18
	v_pk_mul_f32 v[2:3], v[2:3], s[6:7] op_sel_hi:[1,0]
	s_nop 0
	v_cvt_pk_bf16_f32 v150, v2, v3
	v_and_b32_e32 v3, 0xffff0000, v19
	v_lshlrev_b32_e32 v2, 16, v19
	v_pk_mul_f32 v[2:3], v[2:3], s[6:7] op_sel_hi:[1,0]
	s_nop 0
	v_cvt_pk_bf16_f32 v151, v2, v3
	s_waitcnt vmcnt(1)
	v_and_b32_e32 v7, 0xffff0000, v20
	v_lshlrev_b32_e32 v6, 16, v20
	v_pk_mul_f32 v[6:7], v[6:7], s[6:7] op_sel_hi:[1,0]
	s_nop 0
	v_cvt_pk_bf16_f32 v152, v6, v7
	v_and_b32_e32 v7, 0xffff0000, v21
	v_lshlrev_b32_e32 v6, 16, v21
	v_pk_mul_f32 v[2:3], v[6:7], s[6:7] op_sel_hi:[1,0]
	s_nop 0
	v_cvt_pk_bf16_f32 v153, v2, v3
	v_and_b32_e32 v3, 0xffff0000, v22
	v_lshlrev_b32_e32 v2, 16, v22
	v_pk_mul_f32 v[2:3], v[2:3], s[6:7] op_sel_hi:[1,0]
	s_nop 0
	v_cvt_pk_bf16_f32 v154, v2, v3
	v_and_b32_e32 v3, 0xffff0000, v23
	v_lshlrev_b32_e32 v2, 16, v23
	v_pk_mul_f32 v[2:3], v[2:3], s[6:7] op_sel_hi:[1,0]
	s_nop 0
	v_cvt_pk_bf16_f32 v155, v2, v3
	s_waitcnt vmcnt(0)
	v_and_b32_e32 v5, 0xffff0000, v24
	v_lshlrev_b32_e32 v4, 16, v24
	v_pk_mul_f32 v[4:5], v[4:5], s[6:7] op_sel_hi:[1,0]
	s_nop 0
	v_cvt_pk_bf16_f32 v156, v4, v5
	v_and_b32_e32 v5, 0xffff0000, v25
	v_lshlrev_b32_e32 v4, 16, v25
	v_pk_mul_f32 v[0:1], v[4:5], s[6:7] op_sel_hi:[1,0]
	v_lshlrev_b32_e32 v4, 1, v11
	v_cvt_pk_bf16_f32 v157, v0, v1
	v_and_b32_e32 v1, 0xffff0000, v26
	v_lshlrev_b32_e32 v0, 16, v26
	v_pk_mul_f32 v[0:1], v[0:1], s[6:7] op_sel_hi:[1,0]
	s_nop 0
	v_cvt_pk_bf16_f32 v158, v0, v1
	v_and_b32_e32 v1, 0xffff0000, v27
	v_lshlrev_b32_e32 v0, 16, v27
	v_mul_u32_u24_e32 v3, 0x3000, v10
	v_pk_mul_f32 v[0:1], v[0:1], s[6:7] op_sel_hi:[1,0]
	v_lshl_add_u32 v12, s4, 4, v3
	v_and_b32_e32 v3, 51, v11
	v_cvt_pk_bf16_f32 v159, v0, v1
	v_lshlrev_b32_e32 v0, 4, v11
	v_and_or_b32 v3, v4, 8, v3
	v_ashrrev_i32_e32 v1, 3, v11
	v_lshlrev_b32_e32 v3, 1, v3
	v_and_b32_e32 v4, 8, v11
	v_and_b32_e32 v0, 0x70, v0
	s_mulk_i32 s4, 0x480
	s_movk_i32 s6, 0x90
	v_mul_lo_u32 v2, v1, s8
	v_or3_b32 v15, v3, v4, s4
	v_mad_u64_u32 v[8:9], s[4:5], v1, s6, v[0:1]
	v_or_b32_e32 v13, v0, v2
	s_mul_i32 s4, s30, 0xc0000
	v_add_u32_e32 v0, s4, v13
	global_load_dwordx4 v[4:7], v0, s[90:91]
	v_add_u32_e32 v9, s4, v12
	s_mul_i32 s4, s28, 0x300000
	v_add_u32_e32 v16, s4, v13
	s_add_i32 s5, s4, 0x180000
	v_add_u32_e32 v16, 0xc0000, v16
	global_load_dwordx4 v[160:163], v16, s[90:91]
	v_add_u32_e32 v0, s5, v13
	v_add_u32_e32 v201, 0, v8
	global_load_dwordx4 v[0:3], v0, s[90:91]
	v_add_u32_e32 v16, s5, v12
	global_load_dwordx4 v[164:167], v16, s[92:93]
	v_add_u32_e32 v202, 0, v15
	s_cmp_gt_i32 s26, 2
	s_waitcnt vmcnt(3)
	ds_write_b128 v201, v[4:7]
	global_load_dwordx4 v[4:7], v9, s[92:93]
	s_waitcnt vmcnt(0)
	ds_write_b16 v202, v4 offset:18432
	ds_write_b16_d16_hi v202, v4 offset:18576
	ds_write_b16 v202, v5 offset:18720
	ds_write_b16_d16_hi v202, v5 offset:18864
	ds_write_b16 v202, v6 offset:19008
	ds_write_b16_d16_hi v202, v6 offset:19152
	ds_write_b16 v202, v7 offset:19296
	ds_write_b16_d16_hi v202, v7 offset:19440
	v_mad_u32_u24 v4, v14, s6, v128
	v_add_u32_e32 v204, 0, v4
	ds_write_b128 v201, v[0:3] offset:9216
	s_waitcnt lgkmcnt(0)
	s_barrier
	s_cbranch_scc0 .LBB0_204
	v_lshl_or_b32 v0, s30, 6, v200
	v_sub_u32_e32 v0, v199, v0
	v_cvt_f32_i32_e32 v1, v0
	s_mov_b32 s4, 2.0
	s_mov_b32 s5, 0x40400000
	v_mul_f32_e64 v0, -v192, v1
	v_pk_fma_f32 v[34:35], v[192:193], s[4:5], v[0:1] op_sel_hi:[0,1,0]
	s_mov_b32 s4, 0x41000000
	s_mov_b32 s5, 0x41100000
	v_pk_fma_f32 v[36:37], v[192:193], s[4:5], v[0:1] op_sel_hi:[0,1,0]
	s_mov_b32 s4, 0x41200000
	s_mov_b32 s5, 0x41300000
	v_pk_fma_f32 v[38:39], v[192:193], s[4:5], v[0:1] op_sel_hi:[0,1,0]
	s_mov_b32 s4, 0x41800000
	s_mov_b32 s5, 0x41880000
	v_pk_fma_f32 v[40:41], v[192:193], s[4:5], v[0:1] op_sel_hi:[0,1,0]
	s_mov_b32 s4, 0x41900000
	s_mov_b32 s5, 0x41980000
	v_pk_fma_f32 v[42:43], v[192:193], s[4:5], v[0:1] op_sel_hi:[0,1,0]
	s_mov_b32 s4, 0x41c00000
	s_mov_b32 s5, 0x41c80000
	v_pk_fma_f32 v[44:45], v[192:193], s[4:5], v[0:1] op_sel_hi:[0,1,0]
	s_mov_b32 s4, 0x41d00000
	s_mov_b32 s5, 0x41d80000
	v_pk_fma_f32 v[46:47], v[192:193], s[4:5], v[0:1] op_sel_hi:[0,1,0]
	s_mov_b32 s4, 0x42680000
	s_mov_b32 s5, 0x426c0000
	v_pk_fma_f32 v[62:63], v[192:193], s[4:5], v[0:1] op_sel_hi:[0,1,0]
	s_mov_b32 s4, 0x42600000
	s_mov_b32 s5, 0x42640000
	v_pk_fma_f32 v[60:61], v[192:193], s[4:5], v[0:1] op_sel_hi:[0,1,0]
	s_mov_b32 s4, 0x42480000
	s_mov_b32 s5, 0x424c0000
	v_pk_fma_f32 v[58:59], v[192:193], s[4:5], v[0:1] op_sel_hi:[0,1,0]
	s_mov_b32 s4, 0x42400000
	s_mov_b32 s5, 0x42440000
	v_pk_fma_f32 v[56:57], v[192:193], s[4:5], v[0:1] op_sel_hi:[0,1,0]
	s_mov_b32 s4, 0x42280000
	s_mov_b32 s5, 0x422c0000
	v_pk_fma_f32 v[54:55], v[192:193], s[4:5], v[0:1] op_sel_hi:[0,1,0]
	s_mov_b32 s4, 0x42200000
	s_mov_b32 s5, 0x42240000
	v_pk_fma_f32 v[52:53], v[192:193], s[4:5], v[0:1] op_sel_hi:[0,1,0]
	s_mov_b32 s4, 0x42080000
	s_mov_b32 s5, 0x420c0000
	v_pk_fma_f32 v[50:51], v[192:193], s[4:5], v[0:1] op_sel_hi:[0,1,0]
	s_mov_b32 s4, 0x42000000
	s_mov_b32 s5, 0x42040000
	v_fma_f32 v33, -v192, v1, v192
	v_mov_b32_e32 v32, v0
	v_pk_fma_f32 v[48:49], v[192:193], s[4:5], v[0:1] op_sel_hi:[0,1,0]
	ds_read_b128 v[0:3], v204
	ds_read_b128 v[4:7], v204 offset:32
	v_fmac_f32_e32 v32, 0, v192
	s_waitcnt lgkmcnt(1)
	s_nop 0
	v_mfma_f32_32x32x16_bf16 v[32:47], v[0:3], v[144:147], v[32:47]
	ds_read_b128 v[0:3], v204 offset:4608
	s_waitcnt lgkmcnt(0)
	v_mfma_f32_32x32x16_bf16 v[48:63], v[0:3], v[144:147], v[48:63]
	ds_read_b128 v[0:3], v204 offset:4640
	s_waitcnt lgkmcnt(0)
	v_mfma_f32_32x32x16_bf16 v[48:63], v[0:3], v[148:151], v[48:63]
	ds_read_b128 v[0:3], v204 offset:64
	v_mfma_f32_32x32x16_bf16 v[32:47], v[4:7], v[148:151], v[32:47]
	s_waitcnt lgkmcnt(0)
	v_mfma_f32_32x32x16_bf16 v[32:47], v[0:3], v[152:155], v[32:47]
	ds_read_b128 v[0:3], v204 offset:4672
	ds_read_b128 v[4:7], v204 offset:96
	ds_read_b128 v[16:19], v204 offset:4704
	s_waitcnt lgkmcnt(2)
	v_mfma_f32_32x32x16_bf16 v[48:63], v[0:3], v[152:155], v[48:63]
	s_waitcnt lgkmcnt(1)
	v_mfma_f32_32x32x16_bf16 v[32:47], v[4:7], v[156:159], v[32:47]
	s_waitcnt lgkmcnt(0)
	v_mfma_f32_32x32x16_bf16 v[48:63], v[16:19], v[156:159], v[48:63]
	v_mov_b64_e32 v[194:195], v[192:193]
	s_lshl_b32 s22, s29, 6
	s_cbranch_execz .LBB0_205
	s_branch .LBB0_206

.LBB0_212:
	s_or_b32 s19, s25, 1
	s_cmp_lt_u32 s19, s17
	s_cselect_b64 s[88:89], -1, 0
	s_cmp_ge_u32 s19, s17
	s_cbranch_scc1 .LBB0_215
	s_add_i32 s5, s4, -1
	s_cmp_gt_i32 s5, s26
	s_cbranch_scc1 .LBB0_215
	v_lshl_or_b32 v64, s5, 6, v200
	v_sub_u32_e32 v64, v199, v64
	v_cvt_f32_i32_e32 v64, v64
	s_mov_b32 s6, 2.0
	s_mov_b32 s7, 0x40400000
	v_mov_b32_e32 v193, v192
	v_mul_f32_e32 v80, v203, v64
	v_pk_fma_f32 v[66:67], v[194:195], s[6:7], v[80:81] op_sel_hi:[1,1,0]
	s_mov_b32 s6, 0x41000000
	s_mov_b32 s7, 0x41100000
	v_pk_fma_f32 v[68:69], v[194:195], s[6:7], v[80:81] op_sel_hi:[1,1,0]
	s_mov_b32 s6, 0x41200000
	s_mov_b32 s7, 0x41300000
	v_pk_fma_f32 v[70:71], v[194:195], s[6:7], v[80:81] op_sel_hi:[1,1,0]
	s_mov_b32 s6, 0x41800000
	s_mov_b32 s7, 0x41880000
	v_pk_fma_f32 v[72:73], v[194:195], s[6:7], v[80:81] op_sel_hi:[1,1,0]
	s_mov_b32 s6, 0x41900000
	s_mov_b32 s7, 0x41980000
	v_pk_fma_f32 v[74:75], v[194:195], s[6:7], v[80:81] op_sel_hi:[1,1,0]
	s_mov_b32 s6, 0x41c00000
	s_mov_b32 s7, 0x41c80000
	v_pk_fma_f32 v[76:77], v[194:195], s[6:7], v[80:81] op_sel_hi:[1,1,0]
	s_mov_b32 s6, 0x41d00000
	s_mov_b32 s7, 0x41d80000
	v_pk_fma_f32 v[78:79], v[194:195], s[6:7], v[80:81] op_sel_hi:[1,1,0]
	s_mov_b32 s6, 0x42680000
	s_mov_b32 s7, 0x426c0000
	v_pk_fma_f32 v[94:95], v[192:193], s[6:7], v[80:81] op_sel_hi:[1,1,0]
	s_mov_b32 s6, 0x42600000
	s_mov_b32 s7, 0x42640000
	v_pk_fma_f32 v[92:93], v[192:193], s[6:7], v[80:81] op_sel_hi:[1,1,0]
	s_mov_b32 s6, 0x42480000
	ds_read_b128 v[96:99], v204 offset:9216
	ds_read_b128 v[100:103], v204 offset:9248
	s_mov_b32 s7, 0x424c0000
	v_fma_f32 v65, v203, v64, v192
	v_mov_b32_e32 v64, v80
	v_pk_fma_f32 v[90:91], v[192:193], s[6:7], v[80:81] op_sel_hi:[1,1,0]
	s_mov_b32 s6, 0x42400000
	v_fmac_f32_e32 v64, 0, v192
	s_mov_b32 s7, 0x42440000
	v_pk_fma_f32 v[88:89], v[192:193], s[6:7], v[80:81] op_sel_hi:[1,1,0]
	s_mov_b32 s6, 0x42280000
	s_waitcnt lgkmcnt(1)
	v_mfma_f32_32x32x16_bf16 v[64:79], v[96:99], v[144:147], v[64:79]
	ds_read_b128 v[96:99], v204 offset:13824
	s_mov_b32 s7, 0x422c0000
	v_fma_f32 v86, v192, s6, v80
	v_fma_f32 v87, v193, s7, v80
	s_mov_b32 s6, 0x42200000
	s_mov_b32 s7, 0x42240000
	v_pk_fma_f32 v[84:85], v[192:193], s[6:7], v[80:81] op_sel_hi:[1,1,0]
	s_mov_b32 s6, 0x42080000
	s_mov_b32 s7, 0x420c0000
	v_pk_fma_f32 v[82:83], v[192:193], s[6:7], v[80:81] op_sel_hi:[1,1,0]
	s_mov_b32 s6, 0x42000000
	s_mov_b32 s7, 0x42040000
	v_pk_fma_f32 v[80:81], v[196:197], s[6:7], v[80:81] op_sel_hi:[1,1,0]
	s_waitcnt lgkmcnt(1)
	v_mfma_f32_32x32x16_bf16 v[64:79], v[100:103], v[148:151], v[64:79]
	s_waitcnt lgkmcnt(0)
	v_mfma_f32_32x32x16_bf16 v[80:95], v[96:99], v[144:147], v[80:95]
	ds_read_b128 v[96:99], v204 offset:13856
	ds_read_b128 v[136:139], v204 offset:9280
	ds_read_b128 v[140:143], v204 offset:13888
	ds_read_b128 v[244:247], v204 offset:9312
	s_waitcnt lgkmcnt(3)
	v_mfma_f32_32x32x16_bf16 v[80:95], v[96:99], v[148:151], v[80:95]
	ds_read_b128 v[96:99], v204 offset:13920
	s_waitcnt lgkmcnt(3)
	v_mfma_f32_32x32x16_bf16 v[64:79], v[136:139], v[152:155], v[64:79]
	s_waitcnt lgkmcnt(2)
	v_mfma_f32_32x32x16_bf16 v[80:95], v[140:143], v[152:155], v[80:95]
	s_waitcnt lgkmcnt(1)
	v_mfma_f32_32x32x16_bf16 v[64:79], v[244:247], v[156:159], v[64:79]
	s_waitcnt lgkmcnt(0)
	v_mfma_f32_32x32x16_bf16 v[80:95], v[96:99], v[156:159], v[80:95]

.LBB0_226:
	v_sub_f32_e32 v32, v96, v63
	v_exp_f32_e32 v32, v32
	v_sub_f32_e32 v33, v97, v63
	v_exp_f32_e32 v33, v33
	v_add_f32_e32 v34, 0, v32
	v_add_f32_e32 v35, v33, v34
	v_sub_f32_e32 v34, v98, v63
	v_exp_f32_e32 v34, v34
	s_nop 0
	v_add_f32_e32 v36, v34, v35
	v_sub_f32_e32 v35, v99, v63
	v_exp_f32_e32 v35, v35
	s_nop 0
	v_add_f32_e32 v37, v35, v36
	v_sub_f32_e32 v36, v100, v63
	v_exp_f32_e32 v36, v36
	s_nop 0
	v_add_f32_e32 v38, v36, v37
	v_sub_f32_e32 v37, v101, v63
	v_exp_f32_e32 v37, v37
	s_nop 0
	v_add_f32_e32 v39, v37, v38
	v_sub_f32_e32 v38, v102, v63
	v_exp_f32_e32 v38, v38
	s_nop 0
	v_add_f32_e32 v40, v38, v39
	v_sub_f32_e32 v39, v103, v63
	v_exp_f32_e32 v39, v39
	s_nop 0
	v_add_f32_e32 v41, v39, v40
	v_sub_f32_e32 v40, v104, v63
	v_exp_f32_e32 v40, v40
	s_nop 0
	v_add_f32_e32 v42, v40, v41
	v_sub_f32_e32 v41, v105, v63
	v_exp_f32_e32 v41, v41
	s_nop 0
	v_add_f32_e32 v43, v41, v42
	v_sub_f32_e32 v42, v106, v63
	v_exp_f32_e32 v42, v42
	v_cvt_pk_bf16_f32 v104, v40, v41
	v_add_f32_e32 v44, v42, v43
	v_sub_f32_e32 v43, v107, v63
	v_exp_f32_e32 v43, v43
	s_nop 0
	v_add_f32_e32 v45, v43, v44
	v_sub_f32_e32 v44, v108, v63
	v_exp_f32_e32 v44, v44
	v_cvt_pk_bf16_f32 v108, v32, v33
	v_cvt_pk_bf16_f32 v105, v42, v43
	v_add_f32_e32 v46, v44, v45
	v_sub_f32_e32 v45, v109, v63
	v_exp_f32_e32 v45, v45
	v_cvt_pk_bf16_f32 v109, v34, v35
	v_add_f32_e32 v47, v45, v46
	v_sub_f32_e32 v46, v110, v63
	v_exp_f32_e32 v46, v46
	v_cvt_pk_bf16_f32 v110, v36, v37
	v_cvt_pk_bf16_f32 v106, v44, v45
	v_add_f32_e32 v48, v46, v47
	v_sub_f32_e32 v47, v111, v63
	v_exp_f32_e32 v47, v47
	v_cvt_pk_bf16_f32 v111, v38, v39
	v_add_f32_e32 v49, v47, v48
	v_sub_f32_e32 v48, v112, v63
	v_exp_f32_e32 v48, v48
	v_cvt_pk_bf16_f32 v107, v46, v47
	v_add_f32_e32 v50, v48, v49
	v_sub_f32_e32 v49, v113, v63
	v_exp_f32_e32 v49, v49
	s_nop 0
	v_add_f32_e32 v51, v49, v50
	v_sub_f32_e32 v50, v114, v63
	v_exp_f32_e32 v50, v50
	v_cvt_pk_bf16_f32 v100, v48, v49
	v_add_f32_e32 v52, v50, v51
	v_sub_f32_e32 v51, v115, v63
	v_exp_f32_e32 v51, v51
	s_nop 0
	v_add_f32_e32 v53, v51, v52
	v_sub_f32_e32 v52, v116, v63
	v_exp_f32_e32 v52, v52
	v_cvt_pk_bf16_f32 v101, v50, v51
	v_add_f32_e32 v54, v52, v53
	v_sub_f32_e32 v53, v117, v63
	v_exp_f32_e32 v53, v53
	s_nop 0
	v_add_f32_e32 v55, v53, v54
	v_sub_f32_e32 v54, v118, v63
	v_exp_f32_e32 v54, v54
	v_cvt_pk_bf16_f32 v102, v52, v53
	v_add_f32_e32 v56, v54, v55
	v_sub_f32_e32 v55, v119, v63
	v_exp_f32_e32 v55, v55
	s_nop 0
	v_add_f32_e32 v57, v55, v56
	v_sub_f32_e32 v56, v120, v63
	v_exp_f32_e32 v56, v56
	v_cvt_pk_bf16_f32 v103, v54, v55
	v_add_f32_e32 v58, v56, v57
	v_sub_f32_e32 v57, v121, v63
	v_exp_f32_e32 v57, v57
	ds_read_b128 v[114:117], v204 offset:18432
	ds_read_b128 v[118:121], v204 offset:18464
	s_waitcnt lgkmcnt(1)
	v_mfma_f32_32x32x16_bf16 v[16:31], v[114:117], v[108:111], v[16:31]
	v_add_f32_e32 v59, v57, v58
	v_sub_f32_e32 v58, v122, v63
	v_exp_f32_e32 v58, v58
	ds_read_b128 v[114:117], v204 offset:18496
	v_add_f32_e32 v60, v58, v59
	v_sub_f32_e32 v59, v123, v63
	v_exp_f32_e32 v59, v59
	s_waitcnt lgkmcnt(1)
	v_mfma_f32_32x32x16_bf16 v[16:31], v[118:121], v[104:107], v[16:31]
	v_add_f32_e32 v61, v59, v60
	v_sub_f32_e32 v60, v124, v63
	v_exp_f32_e32 v60, v60
	v_cvt_pk_bf16_f32 v97, v58, v59
	v_add_f32_e32 v62, v60, v61
	v_sub_f32_e32 v61, v125, v63
	v_exp_f32_e32 v61, v61
	s_waitcnt lgkmcnt(0)
	v_mfma_f32_32x32x16_bf16 v[16:31], v[114:117], v[100:103], v[16:31]
	ds_read_b128 v[114:117], v204 offset:18528
	v_add_f32_e32 v96, v61, v62
	v_sub_f32_e32 v62, v126, v63
	v_exp_f32_e32 v62, v62
	v_sub_f32_e32 v63, v127, v63
	v_exp_f32_e32 v63, v63
	v_cvt_pk_bf16_f32 v98, v60, v61
	v_add_f32_e32 v96, v62, v96
	v_add_f32_e32 v112, v63, v96
	v_cvt_pk_bf16_f32 v96, v56, v57
	v_cvt_pk_bf16_f32 v99, v62, v63
	v_fmac_f32_e32 v112, v215, v128
	v_mov_b32_e32 v215, v112
	s_waitcnt lgkmcnt(0)
	v_mfma_f32_32x32x16_bf16 v[16:31], v[114:117], v[96:99], v[16:31]
	ds_read_b128 v[114:117], v204 offset:23040
	ds_read_b128 v[136:139], v204 offset:23072
	ds_read_b128 v[140:143], v204 offset:23104
	ds_read_b128 v[244:247], v204 offset:23136
	s_waitcnt lgkmcnt(3)
	v_mfma_f32_32x32x16_bf16 v[0:15], v[114:117], v[108:111], v[0:15]
	s_waitcnt lgkmcnt(2)
	v_mfma_f32_32x32x16_bf16 v[0:15], v[136:139], v[104:107], v[0:15]
	s_waitcnt lgkmcnt(1)
	v_mfma_f32_32x32x16_bf16 v[0:15], v[140:143], v[100:103], v[0:15]
	s_waitcnt lgkmcnt(0)
	v_mfma_f32_32x32x16_bf16 v[0:15], v[244:247], v[96:99], v[0:15]
	v_cndmask_b32_e64 v96, 0, 1, s[86:87]
	v_cmp_ne_u32_e64 s[66:67], 1, v96
	s_andn2_b64 vcc, exec, s[86:87]
	s_cbranch_vccz .LBB0_228
	s_branch .LBB0_229

.LBB0_236:
	s_add_i32 s5, s4, -1
	s_cmp_gt_i32 s5, s26
	s_cbranch_scc1 .LBB0_238
	v_lshl_or_b32 v32, s5, 6, v200
	v_sub_u32_e32 v32, v199, v32
	v_cvt_f32_i32_e32 v32, v32
	s_mov_b32 s6, 2.0
	s_mov_b32 s7, 0x40400000
	v_mov_b32_e32 v193, v192
	v_mul_f32_e32 v48, v203, v32
	v_pk_fma_f32 v[34:35], v[194:195], s[6:7], v[48:49] op_sel_hi:[1,1,0]
	s_mov_b32 s6, 0x41000000
	s_mov_b32 s7, 0x41100000
	v_pk_fma_f32 v[36:37], v[194:195], s[6:7], v[48:49] op_sel_hi:[1,1,0]
	s_mov_b32 s6, 0x41200000
	s_mov_b32 s7, 0x41300000
	v_pk_fma_f32 v[38:39], v[194:195], s[6:7], v[48:49] op_sel_hi:[1,1,0]
	s_mov_b32 s6, 0x41800000
	s_mov_b32 s7, 0x41880000
	v_pk_fma_f32 v[40:41], v[194:195], s[6:7], v[48:49] op_sel_hi:[1,1,0]
	s_mov_b32 s6, 0x41900000
	s_mov_b32 s7, 0x41980000
	v_pk_fma_f32 v[42:43], v[194:195], s[6:7], v[48:49] op_sel_hi:[1,1,0]
	s_mov_b32 s6, 0x41c00000
	s_mov_b32 s7, 0x41c80000
	v_pk_fma_f32 v[44:45], v[194:195], s[6:7], v[48:49] op_sel_hi:[1,1,0]
	s_mov_b32 s6, 0x41d00000
	s_mov_b32 s7, 0x41d80000
	v_pk_fma_f32 v[46:47], v[194:195], s[6:7], v[48:49] op_sel_hi:[1,1,0]
	s_mov_b32 s6, 0x42680000
	s_mov_b32 s7, 0x426c0000
	v_pk_fma_f32 v[62:63], v[192:193], s[6:7], v[48:49] op_sel_hi:[1,1,0]
	s_mov_b32 s6, 0x42600000
	s_mov_b32 s7, 0x42640000
	v_pk_fma_f32 v[60:61], v[192:193], s[6:7], v[48:49] op_sel_hi:[1,1,0]
	s_mov_b32 s6, 0x42480000
	ds_read_b128 v[96:99], v204
	ds_read_b128 v[100:103], v204 offset:32
	s_mov_b32 s7, 0x424c0000
	v_fma_f32 v33, v203, v32, v192
	v_mov_b32_e32 v32, v48
	v_pk_fma_f32 v[58:59], v[192:193], s[6:7], v[48:49] op_sel_hi:[1,1,0]
	s_mov_b32 s6, 0x42400000
	v_fmac_f32_e32 v32, 0, v192
	s_mov_b32 s7, 0x42440000
	v_pk_fma_f32 v[56:57], v[192:193], s[6:7], v[48:49] op_sel_hi:[1,1,0]
	s_mov_b32 s6, 0x42280000
	s_waitcnt lgkmcnt(1)
	v_mfma_f32_32x32x16_bf16 v[32:47], v[96:99], v[144:147], v[32:47]
	ds_read_b128 v[96:99], v204 offset:4608
	s_mov_b32 s7, 0x422c0000
	v_fma_f32 v54, v192, s6, v48
	v_fma_f32 v55, v193, s7, v48
	s_mov_b32 s6, 0x42200000
	s_mov_b32 s7, 0x42240000
	v_pk_fma_f32 v[52:53], v[192:193], s[6:7], v[48:49] op_sel_hi:[1,1,0]
	s_mov_b32 s6, 0x42080000
	s_mov_b32 s7, 0x420c0000
	v_pk_fma_f32 v[50:51], v[192:193], s[6:7], v[48:49] op_sel_hi:[1,1,0]
	s_mov_b32 s6, 0x42000000
	s_mov_b32 s7, 0x42040000
	v_pk_fma_f32 v[48:49], v[196:197], s[6:7], v[48:49] op_sel_hi:[1,1,0]
	s_waitcnt lgkmcnt(1)
	v_mfma_f32_32x32x16_bf16 v[32:47], v[100:103], v[148:151], v[32:47]
	s_waitcnt lgkmcnt(0)
	v_mfma_f32_32x32x16_bf16 v[48:63], v[96:99], v[144:147], v[48:63]
	ds_read_b128 v[96:99], v204 offset:4640
	ds_read_b128 v[136:139], v204 offset:64
	ds_read_b128 v[140:143], v204 offset:4672
	ds_read_b128 v[244:247], v204 offset:96
	s_waitcnt lgkmcnt(3)
	v_mfma_f32_32x32x16_bf16 v[48:63], v[96:99], v[148:151], v[48:63]
	ds_read_b128 v[96:99], v204 offset:4704
	s_waitcnt lgkmcnt(3)
	v_mfma_f32_32x32x16_bf16 v[32:47], v[136:139], v[152:155], v[32:47]
	s_waitcnt lgkmcnt(2)
	v_mfma_f32_32x32x16_bf16 v[48:63], v[140:143], v[152:155], v[48:63]
	s_waitcnt lgkmcnt(1)
	v_mfma_f32_32x32x16_bf16 v[32:47], v[244:247], v[156:159], v[32:47]
	s_waitcnt lgkmcnt(0)
	v_mfma_f32_32x32x16_bf16 v[48:63], v[96:99], v[156:159], v[48:63]

.LBB0_249:
	v_sub_f32_e32 v64, v96, v95
	v_exp_f32_e32 v64, v64
	v_sub_f32_e32 v65, v97, v95
	v_exp_f32_e32 v65, v65
	v_add_f32_e32 v66, 0, v64
	v_add_f32_e32 v67, v65, v66
	v_sub_f32_e32 v66, v98, v95
	v_exp_f32_e32 v66, v66
	s_nop 0
	v_add_f32_e32 v68, v66, v67
	v_sub_f32_e32 v67, v99, v95
	v_exp_f32_e32 v67, v67
	s_nop 0
	v_add_f32_e32 v69, v67, v68
	v_sub_f32_e32 v68, v100, v95
	v_exp_f32_e32 v68, v68
	s_nop 0
	v_add_f32_e32 v70, v68, v69
	v_sub_f32_e32 v69, v101, v95
	v_exp_f32_e32 v69, v69
	s_nop 0
	v_add_f32_e32 v71, v69, v70
	v_sub_f32_e32 v70, v102, v95
	v_exp_f32_e32 v70, v70
	s_nop 0
	v_add_f32_e32 v72, v70, v71
	v_sub_f32_e32 v71, v103, v95
	v_exp_f32_e32 v71, v71
	s_nop 0
	v_add_f32_e32 v73, v71, v72
	v_sub_f32_e32 v72, v104, v95
	v_exp_f32_e32 v72, v72
	s_nop 0
	v_add_f32_e32 v74, v72, v73
	v_sub_f32_e32 v73, v105, v95
	v_exp_f32_e32 v73, v73
	s_nop 0
	v_add_f32_e32 v75, v73, v74
	v_sub_f32_e32 v74, v106, v95
	v_exp_f32_e32 v74, v74
	v_cvt_pk_bf16_f32 v104, v72, v73
	v_add_f32_e32 v76, v74, v75
	v_sub_f32_e32 v75, v107, v95
	v_exp_f32_e32 v75, v75
	s_nop 0
	v_add_f32_e32 v77, v75, v76
	v_sub_f32_e32 v76, v108, v95
	v_exp_f32_e32 v76, v76
	v_cvt_pk_bf16_f32 v108, v64, v65
	v_cvt_pk_bf16_f32 v105, v74, v75
	v_add_f32_e32 v78, v76, v77
	v_sub_f32_e32 v77, v109, v95
	v_exp_f32_e32 v77, v77
	v_cvt_pk_bf16_f32 v109, v66, v67
	v_add_f32_e32 v79, v77, v78
	v_sub_f32_e32 v78, v110, v95
	v_exp_f32_e32 v78, v78
	v_cvt_pk_bf16_f32 v110, v68, v69
	v_cvt_pk_bf16_f32 v106, v76, v77
	v_add_f32_e32 v80, v78, v79
	v_sub_f32_e32 v79, v111, v95
	v_exp_f32_e32 v79, v79
	v_cvt_pk_bf16_f32 v111, v70, v71
	v_add_f32_e32 v81, v79, v80
	v_sub_f32_e32 v80, v112, v95
	v_exp_f32_e32 v80, v80
	v_cvt_pk_bf16_f32 v107, v78, v79
	v_add_f32_e32 v82, v80, v81
	v_sub_f32_e32 v81, v113, v95
	v_exp_f32_e32 v81, v81
	s_nop 0
	v_add_f32_e32 v83, v81, v82
	v_sub_f32_e32 v82, v114, v95
	v_exp_f32_e32 v82, v82
	v_cvt_pk_bf16_f32 v100, v80, v81
	v_add_f32_e32 v84, v82, v83
	v_sub_f32_e32 v83, v115, v95
	v_exp_f32_e32 v83, v83
	s_nop 0
	v_add_f32_e32 v85, v83, v84
	v_sub_f32_e32 v84, v116, v95
	v_exp_f32_e32 v84, v84
	v_cvt_pk_bf16_f32 v101, v82, v83
	v_add_f32_e32 v86, v84, v85
	v_sub_f32_e32 v85, v117, v95
	v_exp_f32_e32 v85, v85
	s_nop 0
	v_add_f32_e32 v87, v85, v86
	v_sub_f32_e32 v86, v118, v95
	v_exp_f32_e32 v86, v86
	v_cvt_pk_bf16_f32 v102, v84, v85
	v_add_f32_e32 v88, v86, v87
	v_sub_f32_e32 v87, v119, v95
	v_exp_f32_e32 v87, v87
	s_nop 0
	v_add_f32_e32 v89, v87, v88
	v_sub_f32_e32 v88, v120, v95
	v_exp_f32_e32 v88, v88
	v_cvt_pk_bf16_f32 v103, v86, v87
	v_add_f32_e32 v90, v88, v89
	v_sub_f32_e32 v89, v121, v95
	v_exp_f32_e32 v89, v89
	ds_read_b128 v[114:117], v204 offset:36864
	ds_read_b128 v[118:121], v204 offset:36896
	s_waitcnt lgkmcnt(1)
	v_mfma_f32_32x32x16_bf16 v[16:31], v[114:117], v[108:111], v[16:31]
	v_add_f32_e32 v91, v89, v90
	v_sub_f32_e32 v90, v122, v95
	v_exp_f32_e32 v90, v90
	ds_read_b128 v[114:117], v204 offset:36928
	v_add_f32_e32 v92, v90, v91
	v_sub_f32_e32 v91, v123, v95
	v_exp_f32_e32 v91, v91
	s_waitcnt lgkmcnt(1)
	v_mfma_f32_32x32x16_bf16 v[16:31], v[118:121], v[104:107], v[16:31]
	v_add_f32_e32 v93, v91, v92
	v_sub_f32_e32 v92, v124, v95
	v_exp_f32_e32 v92, v92
	v_cvt_pk_bf16_f32 v97, v90, v91
	v_add_f32_e32 v94, v92, v93
	v_sub_f32_e32 v93, v125, v95
	v_exp_f32_e32 v93, v93
	s_waitcnt lgkmcnt(0)
	v_mfma_f32_32x32x16_bf16 v[16:31], v[114:117], v[100:103], v[16:31]
	ds_read_b128 v[114:117], v204 offset:36960
	v_add_f32_e32 v96, v93, v94
	v_sub_f32_e32 v94, v126, v95
	v_exp_f32_e32 v94, v94
	v_sub_f32_e32 v95, v127, v95
	v_exp_f32_e32 v95, v95
	v_cvt_pk_bf16_f32 v98, v92, v93
	v_add_f32_e32 v96, v94, v96
	v_add_f32_e32 v112, v95, v96
	v_cvt_pk_bf16_f32 v96, v88, v89
	v_cvt_pk_bf16_f32 v99, v94, v95
	v_fmac_f32_e32 v112, v215, v128
	v_mov_b32_e32 v215, v112
	s_waitcnt lgkmcnt(0)
	v_mfma_f32_32x32x16_bf16 v[16:31], v[114:117], v[96:99], v[16:31]
	ds_read_b128 v[114:117], v204 offset:41472
	ds_read_b128 v[136:139], v204 offset:41504
	ds_read_b128 v[140:143], v204 offset:41536
	ds_read_b128 v[244:247], v204 offset:41568
	s_waitcnt lgkmcnt(3)
	v_mfma_f32_32x32x16_bf16 v[0:15], v[114:117], v[108:111], v[0:15]
	s_waitcnt lgkmcnt(2)
	v_mfma_f32_32x32x16_bf16 v[0:15], v[136:139], v[104:107], v[0:15]
	s_waitcnt lgkmcnt(1)
	v_mfma_f32_32x32x16_bf16 v[0:15], v[140:143], v[100:103], v[0:15]
	s_waitcnt lgkmcnt(0)
	v_mfma_f32_32x32x16_bf16 v[0:15], v[244:247], v[96:99], v[0:15]
	s_and_b64 vcc, exec, s[64:65]
	s_cbranch_vccz .LBB0_253
	s_branch .LBB0_254

.LBB0_261:
	s_add_i32 s5, s4, -1
	s_cmp_gt_i32 s5, s26
	s_cbranch_scc1 .LBB0_263
	v_lshl_or_b32 v64, s5, 6, v200
	v_sub_u32_e32 v64, v199, v64
	v_cvt_f32_i32_e32 v64, v64
	s_mov_b32 s6, 2.0
	s_mov_b32 s7, 0x40400000
	v_mov_b32_e32 v193, v192
	v_mul_f32_e32 v80, v203, v64
	v_pk_fma_f32 v[66:67], v[194:195], s[6:7], v[80:81] op_sel_hi:[1,1,0]
	s_mov_b32 s6, 0x41000000
	s_mov_b32 s7, 0x41100000
	v_pk_fma_f32 v[68:69], v[194:195], s[6:7], v[80:81] op_sel_hi:[1,1,0]
	s_mov_b32 s6, 0x41200000
	s_mov_b32 s7, 0x41300000
	v_pk_fma_f32 v[70:71], v[194:195], s[6:7], v[80:81] op_sel_hi:[1,1,0]
	s_mov_b32 s6, 0x41800000
	s_mov_b32 s7, 0x41880000
	v_pk_fma_f32 v[72:73], v[194:195], s[6:7], v[80:81] op_sel_hi:[1,1,0]
	s_mov_b32 s6, 0x41900000
	s_mov_b32 s7, 0x41980000
	v_pk_fma_f32 v[74:75], v[194:195], s[6:7], v[80:81] op_sel_hi:[1,1,0]
	s_mov_b32 s6, 0x41c00000
	s_mov_b32 s7, 0x41c80000
	v_pk_fma_f32 v[76:77], v[194:195], s[6:7], v[80:81] op_sel_hi:[1,1,0]
	s_mov_b32 s6, 0x41d00000
	s_mov_b32 s7, 0x41d80000
	v_pk_fma_f32 v[78:79], v[194:195], s[6:7], v[80:81] op_sel_hi:[1,1,0]
	s_mov_b32 s6, 0x42680000
	s_mov_b32 s7, 0x426c0000
	v_pk_fma_f32 v[94:95], v[192:193], s[6:7], v[80:81] op_sel_hi:[1,1,0]
	s_mov_b32 s6, 0x42600000
	s_mov_b32 s7, 0x42640000
	v_pk_fma_f32 v[92:93], v[192:193], s[6:7], v[80:81] op_sel_hi:[1,1,0]
	s_mov_b32 s6, 0x42480000
	ds_read_b128 v[96:99], v204 offset:9216
	ds_read_b128 v[100:103], v204 offset:9248
	s_mov_b32 s7, 0x424c0000
	v_fma_f32 v65, v203, v64, v192
	v_mov_b32_e32 v64, v80
	v_pk_fma_f32 v[90:91], v[192:193], s[6:7], v[80:81] op_sel_hi:[1,1,0]
	s_mov_b32 s6, 0x42400000
	v_fmac_f32_e32 v64, 0, v192
	s_mov_b32 s7, 0x42440000
	v_pk_fma_f32 v[88:89], v[192:193], s[6:7], v[80:81] op_sel_hi:[1,1,0]
	s_mov_b32 s6, 0x42280000
	s_waitcnt lgkmcnt(1)
	v_mfma_f32_32x32x16_bf16 v[64:79], v[96:99], v[144:147], v[64:79]
	ds_read_b128 v[96:99], v204 offset:13824
	s_mov_b32 s7, 0x422c0000
	v_fma_f32 v86, v192, s6, v80
	v_fma_f32 v87, v193, s7, v80
	s_mov_b32 s6, 0x42200000
	s_mov_b32 s7, 0x42240000
	v_pk_fma_f32 v[84:85], v[192:193], s[6:7], v[80:81] op_sel_hi:[1,1,0]
	s_mov_b32 s6, 0x42080000
	s_mov_b32 s7, 0x420c0000
	v_pk_fma_f32 v[82:83], v[192:193], s[6:7], v[80:81] op_sel_hi:[1,1,0]
	s_mov_b32 s6, 0x42000000
	s_mov_b32 s7, 0x42040000
	v_pk_fma_f32 v[80:81], v[196:197], s[6:7], v[80:81] op_sel_hi:[1,1,0]
	s_waitcnt lgkmcnt(1)
	v_mfma_f32_32x32x16_bf16 v[64:79], v[100:103], v[148:151], v[64:79]
	s_waitcnt lgkmcnt(0)
	v_mfma_f32_32x32x16_bf16 v[80:95], v[96:99], v[144:147], v[80:95]
	ds_read_b128 v[96:99], v204 offset:13856
	ds_read_b128 v[136:139], v204 offset:9280
	ds_read_b128 v[140:143], v204 offset:13888
	ds_read_b128 v[244:247], v204 offset:9312
	s_waitcnt lgkmcnt(3)
	v_mfma_f32_32x32x16_bf16 v[80:95], v[96:99], v[148:151], v[80:95]
	ds_read_b128 v[96:99], v204 offset:13920
	s_waitcnt lgkmcnt(3)
	v_mfma_f32_32x32x16_bf16 v[64:79], v[136:139], v[152:155], v[64:79]
	s_waitcnt lgkmcnt(2)
	v_mfma_f32_32x32x16_bf16 v[80:95], v[140:143], v[152:155], v[80:95]
	s_waitcnt lgkmcnt(1)
	v_mfma_f32_32x32x16_bf16 v[64:79], v[244:247], v[156:159], v[64:79]
	s_waitcnt lgkmcnt(0)
	v_mfma_f32_32x32x16_bf16 v[80:95], v[96:99], v[156:159], v[80:95]

.LBB0_274:
	v_sub_f32_e32 v32, v96, v63
	v_exp_f32_e32 v32, v32
	v_sub_f32_e32 v33, v97, v63
	v_exp_f32_e32 v33, v33
	v_add_f32_e32 v34, 0, v32
	v_add_f32_e32 v35, v33, v34
	v_sub_f32_e32 v34, v98, v63
	v_exp_f32_e32 v34, v34
	s_nop 0
	v_add_f32_e32 v36, v34, v35
	v_sub_f32_e32 v35, v99, v63
	v_exp_f32_e32 v35, v35
	s_nop 0
	v_add_f32_e32 v37, v35, v36
	v_sub_f32_e32 v36, v100, v63
	v_exp_f32_e32 v36, v36
	s_nop 0
	v_add_f32_e32 v38, v36, v37
	v_sub_f32_e32 v37, v101, v63
	v_exp_f32_e32 v37, v37
	s_nop 0
	v_add_f32_e32 v39, v37, v38
	v_sub_f32_e32 v38, v102, v63
	v_exp_f32_e32 v38, v38
	s_nop 0
	v_add_f32_e32 v40, v38, v39
	v_sub_f32_e32 v39, v103, v63
	v_exp_f32_e32 v39, v39
	s_nop 0
	v_add_f32_e32 v41, v39, v40
	v_sub_f32_e32 v40, v104, v63
	v_exp_f32_e32 v40, v40
	s_nop 0
	v_add_f32_e32 v42, v40, v41
	v_sub_f32_e32 v41, v105, v63
	v_exp_f32_e32 v41, v41
	s_nop 0
	v_add_f32_e32 v43, v41, v42
	v_sub_f32_e32 v42, v106, v63
	v_exp_f32_e32 v42, v42
	v_cvt_pk_bf16_f32 v104, v40, v41
	v_add_f32_e32 v44, v42, v43
	v_sub_f32_e32 v43, v107, v63
	v_exp_f32_e32 v43, v43
	s_nop 0
	v_add_f32_e32 v45, v43, v44
	v_sub_f32_e32 v44, v108, v63
	v_exp_f32_e32 v44, v44
	v_cvt_pk_bf16_f32 v108, v32, v33
	v_cvt_pk_bf16_f32 v105, v42, v43
	v_add_f32_e32 v46, v44, v45
	v_sub_f32_e32 v45, v109, v63
	v_exp_f32_e32 v45, v45
	v_cvt_pk_bf16_f32 v109, v34, v35
	v_add_f32_e32 v47, v45, v46
	v_sub_f32_e32 v46, v110, v63
	v_exp_f32_e32 v46, v46
	v_cvt_pk_bf16_f32 v110, v36, v37
	v_cvt_pk_bf16_f32 v106, v44, v45
	v_add_f32_e32 v48, v46, v47
	v_sub_f32_e32 v47, v111, v63
	v_exp_f32_e32 v47, v47
	v_cvt_pk_bf16_f32 v111, v38, v39
	v_add_f32_e32 v49, v47, v48
	v_sub_f32_e32 v48, v112, v63
	v_exp_f32_e32 v48, v48
	v_cvt_pk_bf16_f32 v107, v46, v47
	v_add_f32_e32 v50, v48, v49
	v_sub_f32_e32 v49, v113, v63
	v_exp_f32_e32 v49, v49
	s_nop 0
	v_add_f32_e32 v51, v49, v50
	v_sub_f32_e32 v50, v114, v63
	v_exp_f32_e32 v50, v50
	v_cvt_pk_bf16_f32 v100, v48, v49
	v_add_f32_e32 v52, v50, v51
	v_sub_f32_e32 v51, v115, v63
	v_exp_f32_e32 v51, v51
	s_nop 0
	v_add_f32_e32 v53, v51, v52
	v_sub_f32_e32 v52, v116, v63
	v_exp_f32_e32 v52, v52
	v_cvt_pk_bf16_f32 v101, v50, v51
	v_add_f32_e32 v54, v52, v53
	v_sub_f32_e32 v53, v117, v63
	v_exp_f32_e32 v53, v53
	s_nop 0
	v_add_f32_e32 v55, v53, v54
	v_sub_f32_e32 v54, v118, v63
	v_exp_f32_e32 v54, v54
	v_cvt_pk_bf16_f32 v102, v52, v53
	v_add_f32_e32 v56, v54, v55
	v_sub_f32_e32 v55, v119, v63
	v_exp_f32_e32 v55, v55
	s_nop 0
	v_add_f32_e32 v57, v55, v56
	v_sub_f32_e32 v56, v120, v63
	v_exp_f32_e32 v56, v56
	v_cvt_pk_bf16_f32 v103, v54, v55
	v_add_f32_e32 v58, v56, v57
	v_sub_f32_e32 v57, v121, v63
	v_exp_f32_e32 v57, v57
	ds_read_b128 v[114:117], v204 offset:18432
	ds_read_b128 v[118:121], v204 offset:18464
	s_waitcnt lgkmcnt(1)
	v_mfma_f32_32x32x16_bf16 v[16:31], v[114:117], v[108:111], v[16:31]
	v_add_f32_e32 v59, v57, v58
	v_sub_f32_e32 v58, v122, v63
	v_exp_f32_e32 v58, v58
	ds_read_b128 v[114:117], v204 offset:18496
	v_add_f32_e32 v60, v58, v59
	v_sub_f32_e32 v59, v123, v63
	v_exp_f32_e32 v59, v59
	s_waitcnt lgkmcnt(1)
	v_mfma_f32_32x32x16_bf16 v[16:31], v[118:121], v[104:107], v[16:31]
	v_add_f32_e32 v61, v59, v60
	v_sub_f32_e32 v60, v124, v63
	v_exp_f32_e32 v60, v60
	v_cvt_pk_bf16_f32 v97, v58, v59
	v_add_f32_e32 v62, v60, v61
	v_sub_f32_e32 v61, v125, v63
	v_exp_f32_e32 v61, v61
	s_waitcnt lgkmcnt(0)
	v_mfma_f32_32x32x16_bf16 v[16:31], v[114:117], v[100:103], v[16:31]
	ds_read_b128 v[114:117], v204 offset:18528
	v_add_f32_e32 v96, v61, v62
	v_sub_f32_e32 v62, v126, v63
	v_exp_f32_e32 v62, v62
	v_sub_f32_e32 v63, v127, v63
	v_exp_f32_e32 v63, v63
	v_cvt_pk_bf16_f32 v98, v60, v61
	v_add_f32_e32 v96, v62, v96
	v_add_f32_e32 v112, v63, v96
	v_cvt_pk_bf16_f32 v96, v56, v57
	v_cvt_pk_bf16_f32 v99, v62, v63
	v_fmac_f32_e32 v112, v215, v128
	v_mov_b32_e32 v215, v112
	s_waitcnt lgkmcnt(0)
	v_mfma_f32_32x32x16_bf16 v[16:31], v[114:117], v[96:99], v[16:31]
	ds_read_b128 v[114:117], v204 offset:23040
	ds_read_b128 v[136:139], v204 offset:23072
	ds_read_b128 v[140:143], v204 offset:23104
	ds_read_b128 v[244:247], v204 offset:23136
	s_waitcnt lgkmcnt(3)
	v_mfma_f32_32x32x16_bf16 v[0:15], v[114:117], v[108:111], v[0:15]
	s_waitcnt lgkmcnt(2)
	v_mfma_f32_32x32x16_bf16 v[0:15], v[136:139], v[104:107], v[0:15]
	s_waitcnt lgkmcnt(1)
	v_mfma_f32_32x32x16_bf16 v[0:15], v[140:143], v[100:103], v[0:15]
	s_waitcnt lgkmcnt(0)
	v_mfma_f32_32x32x16_bf16 v[0:15], v[244:247], v[96:99], v[0:15]
	s_and_b64 vcc, exec, s[66:67]
	s_cbranch_vccz .LBB0_278
	s_branch .LBB0_279

.LBB0_322:
	s_add_i32 s4, s31, -1
	s_add_i32 s5, s76, 1
	s_and_b32 s77, s4, 1
	s_cmp_gt_i32 s5, s74
	s_cbranch_scc1 .LBB0_329
	s_cmp_eq_u32 s77, 0
	v_add_u32_e32 v128, v148, v149
	v_cvt_f32_i32_e32 v64, v128
	s_cselect_b64 s[14:15], -1, 0
	s_and_b64 s[4:5], s[14:15], exec
	s_cselect_b32 s4, 0, 0x2400
	v_add_u32_e32 v135, s4, v147
	s_mov_b32 s4, 2.0
	v_mul_f32_e64 v134, -v190, v64
	s_mov_b32 s5, 0x40400000
	v_pk_fma_f32 v[82:83], v[192:193], s[4:5], v[134:135] op_sel_hi:[1,1,0]
	s_mov_b32 s4, 0x41000000
	s_mov_b32 s5, 0x41100000
	v_pk_fma_f32 v[84:85], v[192:193], s[4:5], v[134:135] op_sel_hi:[1,1,0]
	s_mov_b32 s4, 0x41200000
	s_mov_b32 s5, 0x41300000
	v_pk_fma_f32 v[86:87], v[192:193], s[4:5], v[134:135] op_sel_hi:[1,1,0]
	s_mov_b32 s4, 0x41800000
	s_mov_b32 s5, 0x41880000
	v_pk_fma_f32 v[88:89], v[192:193], s[4:5], v[134:135] op_sel_hi:[1,1,0]
	s_mov_b32 s4, 0x41900000
	s_mov_b32 s5, 0x41980000
	v_pk_fma_f32 v[90:91], v[192:193], s[4:5], v[134:135] op_sel_hi:[1,1,0]
	s_mov_b32 s4, 0x41c00000
	s_mov_b32 s5, 0x41c80000
	v_pk_fma_f32 v[92:93], v[192:193], s[4:5], v[134:135] op_sel_hi:[1,1,0]
	s_mov_b32 s4, 0x41d00000
	s_mov_b32 s5, 0x41d80000
	v_pk_fma_f32 v[94:95], v[192:193], s[4:5], v[134:135] op_sel_hi:[1,1,0]
	s_mov_b32 s4, 0x42680000
	v_mov_b32_e32 v191, v190
	s_mov_b32 s5, 0x426c0000
	v_pk_fma_f32 v[78:79], v[190:191], s[4:5], v[134:135] op_sel_hi:[1,1,0]
	s_mov_b32 s4, 0x42600000
	s_mov_b32 s5, 0x42640000
	v_pk_fma_f32 v[76:77], v[190:191], s[4:5], v[134:135] op_sel_hi:[1,1,0]
	s_mov_b32 s4, 0x42480000
	v_fma_f32 v81, -v190, v64, v190
	ds_read_b128 v[64:67], v135
	ds_read_b128 v[130:133], v135 offset:4608
	s_mov_b32 s5, 0x424c0000
	v_pk_fma_f32 v[74:75], v[190:191], s[4:5], v[134:135] op_sel_hi:[1,1,0]
	s_mov_b32 s4, 0x42400000
	s_mov_b32 s5, 0x42440000
	v_pk_fma_f32 v[72:73], v[190:191], s[4:5], v[134:135] op_sel_hi:[1,1,0]
	s_mov_b32 s4, 0x42280000
	s_mov_b32 s5, 0x422c0000
	v_pk_fma_f32 v[70:71], v[190:191], s[4:5], v[134:135] op_sel_hi:[1,1,0]
	s_mov_b32 s4, 0x42200000
	s_mov_b32 s5, 0x42240000
	v_mov_b32_e32 v80, v134
	v_pk_fma_f32 v[68:69], v[190:191], s[4:5], v[134:135] op_sel_hi:[1,1,0]
	s_mov_b32 s4, 0x42080000
	v_fmac_f32_e32 v80, 0, v190
	s_mov_b32 s5, 0x420c0000
	v_cmp_ge_i32_e32 vcc, s21, v150
	s_waitcnt lgkmcnt(1)
	v_mfma_f32_32x32x16_bf16 v[80:95], v[64:67], v[96:99], v[80:95]
	v_fma_f32 v66, v190, s4, v134
	v_fma_f32 v67, v191, s5, v134
	s_mov_b32 s4, 0x42000000
	s_mov_b32 s5, 0x42040000
	v_fma_f32 v64, v194, s4, v134
	v_fma_f32 v65, v195, s5, v134
	s_and_b64 vcc, exec, vcc
	s_waitcnt lgkmcnt(0)
	v_mfma_f32_32x32x16_bf16 v[64:79], v[130:133], v[96:99], v[64:79]
	ds_read_b128 v[130:133], v135 offset:32
	ds_read_b128 v[136:139], v135 offset:4640
	ds_read_b128 v[140:143], v135 offset:64
	ds_read_b128 v[152:155], v135 offset:4672
	s_waitcnt lgkmcnt(3)
	v_mfma_f32_32x32x16_bf16 v[80:95], v[130:133], v[100:103], v[80:95]
	ds_read_b128 v[130:133], v135 offset:96
	s_waitcnt lgkmcnt(3)
	v_mfma_f32_32x32x16_bf16 v[64:79], v[136:139], v[100:103], v[64:79]
	ds_read_b128 v[136:139], v135 offset:4704
	s_waitcnt lgkmcnt(3)
	v_mfma_f32_32x32x16_bf16 v[80:95], v[140:143], v[104:107], v[80:95]
	s_waitcnt lgkmcnt(2)
	v_mfma_f32_32x32x16_bf16 v[64:79], v[152:155], v[104:107], v[64:79]
	s_waitcnt lgkmcnt(1)
	v_mfma_f32_32x32x16_bf16 v[80:95], v[130:133], v[108:111], v[80:95]
	s_waitcnt lgkmcnt(0)
	v_mfma_f32_32x32x16_bf16 v[64:79], v[136:139], v[108:111], v[64:79]
	s_cbranch_vccnz .LBB0_325
	v_cmp_gt_i32_e32 vcc, 0, v128
	v_cmp_gt_i32_e64 s[4:5], 1, v128
	s_and_b64 vcc, s[4:5], vcc
	s_nop 4
	v_cndmask_b32_e32 v80, v80, v252, vcc
	v_cmp_lt_i32_e32 vcc, 1, v128
	v_cmp_gt_i32_e64 s[60:61], 58, v128
	v_cmp_gt_i32_e64 s[62:63], 59, v128
	v_cndmask_b32_e32 v82, v252, v82, vcc
	v_cmp_lt_i32_e32 vcc, 2, v128
	v_cmp_gt_i32_e64 s[58:59], 57, v128
	s_and_b64 s[60:61], s[62:63], s[60:61]
	v_cndmask_b32_e32 v83, v252, v83, vcc
	v_cmp_lt_i32_e32 vcc, 7, v128
	v_cmp_gt_i32_e64 s[56:57], 56, v128
	s_and_b64 s[58:59], s[60:61], s[58:59]
	v_cndmask_b32_e32 v84, v252, v84, vcc
	v_cmp_lt_i32_e32 vcc, 8, v128
	v_cmp_gt_i32_e64 s[54:55], 51, v128
	s_and_b64 s[56:57], s[58:59], s[56:57]
	v_cndmask_b32_e32 v85, v252, v85, vcc
	v_cmp_lt_i32_e32 vcc, 9, v128
	v_cmp_gt_i32_e64 s[52:53], 50, v128
	s_and_b64 s[54:55], s[56:57], s[54:55]
	v_cndmask_b32_e32 v86, v252, v86, vcc
	v_cmp_lt_i32_e32 vcc, 10, v128
	v_cmp_gt_i32_e64 s[50:51], 49, v128
	s_and_b64 s[52:53], s[54:55], s[52:53]
	v_cndmask_b32_e32 v87, v252, v87, vcc
	v_cmp_lt_i32_e32 vcc, 15, v128
	v_cmp_gt_i32_e64 s[48:49], 48, v128
	s_and_b64 s[50:51], s[52:53], s[50:51]
	v_cndmask_b32_e32 v88, v252, v88, vcc
	v_cmp_lt_i32_e32 vcc, 16, v128
	v_cmp_gt_i32_e64 s[46:47], 43, v128
	s_and_b64 s[48:49], s[50:51], s[48:49]
	v_cndmask_b32_e32 v89, v252, v89, vcc
	v_cmp_lt_i32_e32 vcc, 17, v128
	v_cmp_gt_i32_e64 s[44:45], 42, v128
	s_and_b64 s[46:47], s[48:49], s[46:47]
	v_cndmask_b32_e32 v90, v252, v90, vcc
	v_cmp_lt_i32_e32 vcc, 18, v128
	v_cmp_gt_i32_e64 s[42:43], 41, v128
	s_and_b64 s[44:45], s[46:47], s[44:45]
	v_cndmask_b32_e32 v91, v252, v91, vcc
	v_cmp_lt_i32_e32 vcc, 23, v128
	v_cmp_gt_i32_e64 s[10:11], 40, v128
	s_and_b64 s[42:43], s[44:45], s[42:43]
	v_cndmask_b32_e32 v92, v252, v92, vcc
	v_cmp_lt_i32_e32 vcc, 24, v128
	v_cmp_gt_i32_e64 s[8:9], 35, v128
	s_and_b64 s[10:11], s[42:43], s[10:11]
	v_cndmask_b32_e32 v93, v252, v93, vcc
	v_cmp_lt_i32_e32 vcc, 25, v128
	v_cmp_gt_i32_e64 s[6:7], 34, v128
	s_and_b64 s[8:9], s[10:11], s[8:9]
	v_cndmask_b32_e64 v81, v81, v252, s[4:5]
	v_cndmask_b32_e32 v94, v252, v94, vcc
	v_cmp_lt_i32_e32 vcc, 26, v128
	v_cmp_gt_i32_e64 s[4:5], 33, v128
	s_and_b64 s[6:7], s[8:9], s[6:7]
	v_cndmask_b32_e32 v130, v252, v95, vcc
	v_cmp_gt_i32_e32 vcc, 32, v128
	s_and_b64 s[4:5], s[6:7], s[4:5]
	s_and_b64 vcc, s[4:5], vcc
	v_cndmask_b32_e64 v79, v79, v252, s[62:63]
	v_cndmask_b32_e64 v78, v78, v252, s[60:61]
	v_cndmask_b32_e64 v77, v77, v252, s[58:59]
	v_cndmask_b32_e64 v76, v76, v252, s[56:57]
	v_cndmask_b32_e64 v75, v75, v252, s[54:55]
	v_cndmask_b32_e64 v74, v74, v252, s[52:53]
	v_cndmask_b32_e64 v73, v73, v252, s[50:51]
	v_cndmask_b32_e64 v72, v72, v252, s[48:49]
	v_cndmask_b32_e64 v71, v71, v252, s[46:47]
	v_cndmask_b32_e64 v70, v70, v252, s[44:45]
	v_cndmask_b32_e64 v69, v69, v252, s[42:43]
	v_cndmask_b32_e64 v68, v68, v252, s[10:11]
	v_cndmask_b32_e64 v67, v67, v252, s[8:9]
	v_cndmask_b32_e64 v66, v66, v252, s[6:7]
	v_cndmask_b32_e64 v65, v65, v252, s[4:5]
	v_cndmask_b32_e32 v95, v95, v130, vcc
	v_cndmask_b32_e32 v64, v64, v252, vcc

.LBB0_327:
	v_sub_f32_e32 v80, v80, v131
	v_exp_f32_e32 v132, v80
	v_sub_f32_e32 v81, v81, v131
	v_exp_f32_e32 v81, v81
	v_sub_f32_e32 v82, v82, v131
	v_exp_f32_e32 v82, v82
	v_sub_f32_e32 v83, v83, v131
	v_exp_f32_e32 v83, v83
	v_sub_f32_e32 v84, v84, v131
	v_add_f32_e32 v80, 0, v132
	v_exp_f32_e32 v84, v84
	v_sub_f32_e32 v85, v85, v131
	v_add_f32_e32 v80, v81, v80
	v_exp_f32_e32 v85, v85
	v_sub_f32_e32 v86, v86, v131
	v_add_f32_e32 v80, v82, v80
	v_exp_f32_e32 v86, v86
	v_sub_f32_e32 v87, v87, v131
	v_sub_f32_e32 v69, v69, v131
	v_add_f32_e32 v80, v83, v80
	v_exp_f32_e32 v87, v87
	v_sub_f32_e32 v88, v88, v131
	v_exp_f32_e32 v134, v69
	v_sub_f32_e32 v69, v70, v131
	v_add_f32_e32 v80, v84, v80
	v_exp_f32_e32 v88, v88
	v_sub_f32_e32 v89, v89, v131
	v_exp_f32_e32 v135, v69
	v_sub_f32_e32 v69, v71, v131
	v_add_f32_e32 v80, v85, v80
	v_exp_f32_e32 v89, v89
	v_sub_f32_e32 v90, v90, v131
	v_exp_f32_e32 v71, v69
	v_sub_f32_e32 v69, v72, v131
	v_add_f32_e32 v80, v86, v80
	v_exp_f32_e32 v90, v90
	v_sub_f32_e32 v91, v91, v131
	v_exp_f32_e32 v136, v69
	v_sub_f32_e32 v69, v73, v131
	v_add_f32_e32 v80, v87, v80
	v_exp_f32_e32 v91, v91
	v_sub_f32_e32 v92, v92, v131
	v_exp_f32_e32 v137, v69
	v_sub_f32_e32 v69, v74, v131
	v_add_f32_e32 v80, v88, v80
	v_exp_f32_e32 v92, v92
	v_sub_f32_e32 v93, v93, v131
	v_exp_f32_e32 v138, v69
	v_sub_f32_e32 v69, v75, v131
	s_and_b64 s[4:5], s[14:15], exec
	v_add_f32_e32 v80, v89, v80
	v_exp_f32_e32 v93, v93
	v_sub_f32_e32 v94, v94, v131
	v_exp_f32_e32 v139, v69
	v_sub_f32_e32 v69, v76, v131
	s_movk_i32 s4, 0x4800
	v_add_f32_e32 v80, v90, v80
	v_exp_f32_e32 v94, v94
	v_sub_f32_e32 v95, v95, v131
	v_exp_f32_e32 v140, v69
	v_sub_f32_e32 v69, v77, v131
	s_cselect_b32 s4, s4, 0x9000
	v_add_f32_e32 v80, v91, v80
	v_exp_f32_e32 v95, v95
	v_sub_f32_e32 v64, v64, v131
	v_exp_f32_e32 v141, v69
	v_sub_f32_e32 v69, v78, v131
	v_cvt_pk_bf16_f32 v76, v132, v81
	v_add_u32_e32 v81, s4, v147
	v_add_f32_e32 v80, v92, v80
	v_exp_f32_e32 v64, v64
	v_sub_f32_e32 v65, v65, v131
	v_exp_f32_e32 v142, v69
	v_sub_f32_e32 v69, v79, v131
	v_cvt_pk_bf16_f32 v77, v82, v83
	v_cvt_pk_bf16_f32 v78, v84, v85
	v_cvt_pk_bf16_f32 v79, v86, v87
	v_cvt_pk_bf16_f32 v72, v88, v89
	ds_read_b128 v[82:85], v81
	ds_read_b128 v[86:89], v81 offset:32
	v_add_f32_e32 v80, v93, v80
	v_exp_f32_e32 v65, v65
	v_sub_f32_e32 v66, v66, v131
	v_add_f32_e32 v80, v94, v80
	v_exp_f32_e32 v66, v66
	v_sub_f32_e32 v67, v67, v131
	v_add_f32_e32 v80, v95, v80
	v_exp_f32_e32 v67, v67
	v_sub_f32_e32 v68, v68, v131
	v_add_f32_e32 v80, v64, v80
	v_exp_f32_e32 v133, v68
	s_waitcnt lgkmcnt(1)
	v_mfma_f32_32x32x16_bf16 v[48:63], v[82:85], v[76:79], v[48:63]
	v_add_f32_e32 v80, v65, v80
	v_add_f32_e32 v80, v66, v80
	v_add_f32_e32 v80, v67, v80
	v_add_f32_e32 v68, v133, v80
	v_add_f32_e32 v68, v134, v68
	v_add_f32_e32 v68, v135, v68
	v_add_f32_e32 v68, v71, v68
	v_cvt_pk_bf16_f32 v73, v90, v91
	v_cvt_pk_bf16_f32 v74, v92, v93
	v_cvt_pk_bf16_f32 v75, v94, v95
	ds_read_b128 v[82:85], v81 offset:64
	v_add_f32_e32 v68, v136, v68
	s_waitcnt lgkmcnt(1)
	v_mfma_f32_32x32x16_bf16 v[48:63], v[86:89], v[72:75], v[48:63]
	v_add_f32_e32 v68, v137, v68
	v_add_f32_e32 v68, v138, v68
	v_add_f32_e32 v68, v139, v68
	v_exp_f32_e32 v131, v69
	v_add_f32_e32 v68, v140, v68
	v_add_f32_e32 v68, v141, v68
	v_add_f32_e32 v68, v142, v68
	v_add_f32_e32 v80, v131, v68
	v_cvt_pk_bf16_f32 v68, v64, v65
	v_cvt_pk_bf16_f32 v69, v66, v67
	v_cvt_pk_bf16_f32 v70, v133, v134
	v_cvt_pk_bf16_f32 v71, v135, v71
	v_cvt_pk_bf16_f32 v64, v136, v137
	v_cvt_pk_bf16_f32 v65, v138, v139
	s_waitcnt lgkmcnt(0)
	v_mfma_f32_32x32x16_bf16 v[48:63], v[82:85], v[68:71], v[48:63]
	ds_read_b128 v[82:85], v81 offset:96
	v_cvt_pk_bf16_f32 v66, v140, v141
	v_cvt_pk_bf16_f32 v67, v142, v131
	v_fmac_f32_e32 v80, v196, v128
	v_mov_b32_e32 v196, v80
	s_waitcnt lgkmcnt(0)
	v_mfma_f32_32x32x16_bf16 v[48:63], v[82:85], v[64:67], v[48:63]
	ds_read_b128 v[82:85], v81 offset:4608
	ds_read_b128 v[88:91], v81 offset:4640
	ds_read_b128 v[92:95], v81 offset:4672
	ds_read_b128 v[132:135], v81 offset:4704
	s_waitcnt lgkmcnt(3)
	v_mfma_f32_32x32x16_bf16 v[32:47], v[82:85], v[76:79], v[32:47]
	ds_read_b128 v[82:85], v81 offset:9216
	s_waitcnt lgkmcnt(3)
	v_mfma_f32_32x32x16_bf16 v[32:47], v[88:91], v[72:75], v[32:47]
	ds_read_b128 v[88:91], v81 offset:9248
	s_waitcnt lgkmcnt(3)
	v_mfma_f32_32x32x16_bf16 v[32:47], v[92:95], v[68:71], v[32:47]
	ds_read_b128 v[92:95], v81 offset:9280
	s_waitcnt lgkmcnt(3)
	v_mfma_f32_32x32x16_bf16 v[32:47], v[132:135], v[64:67], v[32:47]
	ds_read_b128 v[132:135], v81 offset:9312
	s_waitcnt lgkmcnt(3)
	v_mfma_f32_32x32x16_bf16 v[16:31], v[82:85], v[76:79], v[16:31]
	ds_read_b128 v[82:85], v81 offset:13824
	s_waitcnt lgkmcnt(3)
	v_mfma_f32_32x32x16_bf16 v[16:31], v[88:91], v[72:75], v[16:31]
	ds_read_b128 v[88:91], v81 offset:13856
	s_waitcnt lgkmcnt(3)
	v_mfma_f32_32x32x16_bf16 v[16:31], v[92:95], v[68:71], v[16:31]
	ds_read_b128 v[92:95], v81 offset:13888
	s_waitcnt lgkmcnt(3)
	v_mfma_f32_32x32x16_bf16 v[16:31], v[132:135], v[64:67], v[16:31]
	ds_read_b128 v[132:135], v81 offset:13920
	s_waitcnt lgkmcnt(3)
	v_mfma_f32_32x32x16_bf16 v[0:15], v[82:85], v[76:79], v[0:15]
	s_waitcnt lgkmcnt(2)
	v_mfma_f32_32x32x16_bf16 v[0:15], v[88:91], v[72:75], v[0:15]
	s_waitcnt lgkmcnt(1)
	v_mfma_f32_32x32x16_bf16 v[0:15], v[92:95], v[68:71], v[0:15]
	s_waitcnt lgkmcnt(0)
	v_mfma_f32_32x32x16_bf16 v[0:15], v[132:135], v[64:67], v[0:15]
	s_andn2_b64 vcc, exec, s[72:73]
	s_cbranch_vccz .LBB0_330
	s_branch .LBB0_331

.LBB0_345:
	s_add_i32 s4, s23, -1
	s_add_i32 s5, s18, 1
	s_and_b32 s24, s4, 1
	s_cmp_gt_i32 s5, s19
	s_cbranch_scc1 .LBB0_352
	s_cmp_eq_u32 s24, 0
	v_add_u32_e32 v128, v209, v210
	v_cvt_f32_i32_e32 v130, v128
	s_cselect_b64 s[14:15], -1, 0
	s_and_b64 s[4:5], s[14:15], exec
	s_cselect_b32 s4, 0, 0x2400
	v_add_u32_e32 v213, s4, v208
	s_mov_b32 s4, 2.0
	v_mul_f32_e64 v218, -v190, v130
	s_mov_b32 s5, 0x40400000
	v_pk_fma_f32 v[148:149], v[192:193], s[4:5], v[218:219] op_sel_hi:[1,1,0]
	s_mov_b32 s4, 0x41000000
	s_mov_b32 s5, 0x41100000
	v_pk_fma_f32 v[150:151], v[192:193], s[4:5], v[218:219] op_sel_hi:[1,1,0]
	s_mov_b32 s4, 0x41200000
	s_mov_b32 s5, 0x41300000
	v_pk_fma_f32 v[152:153], v[192:193], s[4:5], v[218:219] op_sel_hi:[1,1,0]
	s_mov_b32 s4, 0x41800000
	s_mov_b32 s5, 0x41880000
	v_pk_fma_f32 v[154:155], v[192:193], s[4:5], v[218:219] op_sel_hi:[1,1,0]
	s_mov_b32 s4, 0x41900000
	s_mov_b32 s5, 0x41980000
	v_pk_fma_f32 v[156:157], v[192:193], s[4:5], v[218:219] op_sel_hi:[1,1,0]
	s_mov_b32 s4, 0x41c00000
	s_mov_b32 s5, 0x41c80000
	v_pk_fma_f32 v[158:159], v[192:193], s[4:5], v[218:219] op_sel_hi:[1,1,0]
	s_mov_b32 s4, 0x41d00000
	s_mov_b32 s5, 0x41d80000
	v_pk_fma_f32 v[160:161], v[192:193], s[4:5], v[218:219] op_sel_hi:[1,1,0]
	s_mov_b32 s4, 0x42680000
	v_mov_b32_e32 v191, v190
	s_mov_b32 s5, 0x426c0000
	v_pk_fma_f32 v[144:145], v[190:191], s[4:5], v[218:219] op_sel_hi:[1,1,0]
	s_mov_b32 s4, 0x42600000
	s_mov_b32 s5, 0x42640000
	v_pk_fma_f32 v[142:143], v[190:191], s[4:5], v[218:219] op_sel_hi:[1,1,0]
	s_mov_b32 s4, 0x42480000
	v_fma_f32 v147, -v190, v130, v190
	ds_read_b128 v[130:133], v213
	ds_read_b128 v[214:217], v213 offset:4608
	s_mov_b32 s5, 0x424c0000
	v_pk_fma_f32 v[140:141], v[190:191], s[4:5], v[218:219] op_sel_hi:[1,1,0]
	s_mov_b32 s4, 0x42400000
	s_mov_b32 s5, 0x42440000
	v_pk_fma_f32 v[138:139], v[190:191], s[4:5], v[218:219] op_sel_hi:[1,1,0]
	s_mov_b32 s4, 0x42280000
	s_mov_b32 s5, 0x422c0000
	v_pk_fma_f32 v[136:137], v[190:191], s[4:5], v[218:219] op_sel_hi:[1,1,0]
	s_mov_b32 s4, 0x42200000
	s_mov_b32 s5, 0x42240000
	v_mov_b32_e32 v146, v218
	v_pk_fma_f32 v[134:135], v[190:191], s[4:5], v[218:219] op_sel_hi:[1,1,0]
	s_mov_b32 s4, 0x42080000
	v_fmac_f32_e32 v146, 0, v190
	s_mov_b32 s5, 0x420c0000
	v_cmp_ge_i32_e32 vcc, s21, v211
	s_waitcnt lgkmcnt(1)
	v_mfma_f32_32x32x16_bf16 v[146:161], v[130:133], v[162:165], v[146:161]
	v_fma_f32 v132, v190, s4, v218
	v_fma_f32 v133, v191, s5, v218
	s_mov_b32 s4, 0x42000000
	s_mov_b32 s5, 0x42040000
	v_fma_f32 v130, v194, s4, v218
	v_fma_f32 v131, v195, s5, v218
	s_and_b64 vcc, exec, vcc
	s_waitcnt lgkmcnt(0)
	v_mfma_f32_32x32x16_bf16 v[130:145], v[214:217], v[162:165], v[130:145]
	ds_read_b128 v[214:217], v213 offset:32
	ds_read_b128 v[220:223], v213 offset:4640
	ds_read_b128 v[244:247], v213 offset:64
	s_waitcnt lgkmcnt(2)
	v_mfma_f32_32x32x16_bf16 v[146:161], v[214:217], v[166:169], v[146:161]
	ds_read_b128 v[214:217], v213 offset:4672
	s_waitcnt lgkmcnt(2)
	v_mfma_f32_32x32x16_bf16 v[130:145], v[220:223], v[166:169], v[130:145]
	ds_read_b128 v[220:223], v213 offset:96
	s_waitcnt lgkmcnt(2)
	v_mfma_f32_32x32x16_bf16 v[146:161], v[244:247], v[170:173], v[146:161]
	ds_read_b128 v[244:247], v213 offset:4704
	s_waitcnt lgkmcnt(2)
	v_mfma_f32_32x32x16_bf16 v[130:145], v[214:217], v[170:173], v[130:145]
	s_waitcnt lgkmcnt(1)
	v_mfma_f32_32x32x16_bf16 v[146:161], v[220:223], v[174:177], v[146:161]
	s_waitcnt lgkmcnt(0)
	v_mfma_f32_32x32x16_bf16 v[130:145], v[244:247], v[174:177], v[130:145]
	s_cbranch_vccnz .LBB0_348
	v_cmp_gt_i32_e32 vcc, 0, v128
	v_cmp_gt_i32_e64 s[4:5], 1, v128
	s_and_b64 vcc, s[4:5], vcc
	s_nop 4
	v_cndmask_b32_e32 v146, v146, v252, vcc
	v_cmp_lt_i32_e32 vcc, 1, v128
	v_cmp_gt_i32_e64 s[62:63], 58, v128
	v_cmp_gt_i32_e64 s[64:65], 59, v128
	v_cndmask_b32_e32 v148, v252, v148, vcc
	v_cmp_lt_i32_e32 vcc, 2, v128
	v_cmp_gt_i32_e64 s[60:61], 57, v128
	s_and_b64 s[62:63], s[64:65], s[62:63]
	v_cndmask_b32_e32 v149, v252, v149, vcc
	v_cmp_lt_i32_e32 vcc, 7, v128
	v_cmp_gt_i32_e64 s[58:59], 56, v128
	s_and_b64 s[60:61], s[62:63], s[60:61]
	v_cndmask_b32_e32 v150, v252, v150, vcc
	v_cmp_lt_i32_e32 vcc, 8, v128
	v_cmp_gt_i32_e64 s[56:57], 51, v128
	s_and_b64 s[58:59], s[60:61], s[58:59]
	v_cndmask_b32_e32 v151, v252, v151, vcc
	v_cmp_lt_i32_e32 vcc, 9, v128
	v_cmp_gt_i32_e64 s[54:55], 50, v128
	s_and_b64 s[56:57], s[58:59], s[56:57]
	v_cndmask_b32_e32 v152, v252, v152, vcc
	v_cmp_lt_i32_e32 vcc, 10, v128
	v_cmp_gt_i32_e64 s[52:53], 49, v128
	s_and_b64 s[54:55], s[56:57], s[54:55]
	v_cndmask_b32_e32 v153, v252, v153, vcc
	v_cmp_lt_i32_e32 vcc, 15, v128
	v_cmp_gt_i32_e64 s[50:51], 48, v128
	s_and_b64 s[52:53], s[54:55], s[52:53]
	v_cndmask_b32_e32 v154, v252, v154, vcc
	v_cmp_lt_i32_e32 vcc, 16, v128
	v_cmp_gt_i32_e64 s[48:49], 43, v128
	s_and_b64 s[50:51], s[52:53], s[50:51]
	v_cndmask_b32_e32 v155, v252, v155, vcc
	v_cmp_lt_i32_e32 vcc, 17, v128
	v_cmp_gt_i32_e64 s[46:47], 42, v128
	s_and_b64 s[48:49], s[50:51], s[48:49]
	v_cndmask_b32_e32 v156, v252, v156, vcc
	v_cmp_lt_i32_e32 vcc, 18, v128
	v_cmp_gt_i32_e64 s[44:45], 41, v128
	s_and_b64 s[46:47], s[48:49], s[46:47]
	v_cndmask_b32_e32 v157, v252, v157, vcc
	v_cmp_lt_i32_e32 vcc, 23, v128
	v_cmp_gt_i32_e64 s[10:11], 40, v128
	s_and_b64 s[44:45], s[46:47], s[44:45]
	v_cndmask_b32_e32 v158, v252, v158, vcc
	v_cmp_lt_i32_e32 vcc, 24, v128
	v_cmp_gt_i32_e64 s[8:9], 35, v128
	s_and_b64 s[10:11], s[44:45], s[10:11]
	v_cndmask_b32_e32 v159, v252, v159, vcc
	v_cmp_lt_i32_e32 vcc, 25, v128
	v_cmp_gt_i32_e64 s[6:7], 34, v128
	s_and_b64 s[8:9], s[10:11], s[8:9]
	v_cndmask_b32_e64 v147, v147, v252, s[4:5]
	v_cndmask_b32_e32 v160, v252, v160, vcc
	v_cmp_lt_i32_e32 vcc, 26, v128
	v_cmp_gt_i32_e64 s[4:5], 33, v128
	s_and_b64 s[6:7], s[8:9], s[6:7]
	v_cndmask_b32_e32 v191, v252, v161, vcc
	v_cmp_gt_i32_e32 vcc, 32, v128
	s_and_b64 s[4:5], s[6:7], s[4:5]
	s_and_b64 vcc, s[4:5], vcc
	v_cndmask_b32_e64 v145, v145, v252, s[64:65]
	v_cndmask_b32_e64 v144, v144, v252, s[62:63]
	v_cndmask_b32_e64 v143, v143, v252, s[60:61]
	v_cndmask_b32_e64 v142, v142, v252, s[58:59]
	v_cndmask_b32_e64 v141, v141, v252, s[56:57]
	v_cndmask_b32_e64 v140, v140, v252, s[54:55]
	v_cndmask_b32_e64 v139, v139, v252, s[52:53]
	v_cndmask_b32_e64 v138, v138, v252, s[50:51]
	v_cndmask_b32_e64 v137, v137, v252, s[48:49]
	v_cndmask_b32_e64 v136, v136, v252, s[46:47]
	v_cndmask_b32_e64 v135, v135, v252, s[44:45]
	v_cndmask_b32_e64 v134, v134, v252, s[10:11]
	v_cndmask_b32_e64 v133, v133, v252, s[8:9]
	v_cndmask_b32_e64 v132, v132, v252, s[6:7]
	v_cndmask_b32_e64 v131, v131, v252, s[4:5]
	v_cndmask_b32_e32 v161, v161, v191, vcc
	v_cndmask_b32_e32 v130, v130, v252, vcc

.LBB0_350:
	v_sub_f32_e32 v146, v146, v213
	v_exp_f32_e32 v212, v146
	v_sub_f32_e32 v147, v147, v213
	v_exp_f32_e32 v147, v147
	v_sub_f32_e32 v148, v148, v213
	v_exp_f32_e32 v148, v148
	v_sub_f32_e32 v149, v149, v213
	v_exp_f32_e32 v149, v149
	v_sub_f32_e32 v150, v150, v213
	v_add_f32_e32 v146, 0, v212
	v_exp_f32_e32 v150, v150
	v_sub_f32_e32 v151, v151, v213
	v_add_f32_e32 v146, v147, v146
	v_exp_f32_e32 v151, v151
	v_sub_f32_e32 v152, v152, v213
	v_add_f32_e32 v146, v148, v146
	v_exp_f32_e32 v152, v152
	v_sub_f32_e32 v153, v153, v213
	v_add_f32_e32 v146, v149, v146
	v_exp_f32_e32 v153, v153
	v_sub_f32_e32 v154, v154, v213
	v_add_f32_e32 v146, v150, v146
	v_exp_f32_e32 v154, v154
	v_sub_f32_e32 v155, v155, v213
	v_add_f32_e32 v146, v151, v146
	v_exp_f32_e32 v155, v155
	v_sub_f32_e32 v156, v156, v213
	v_add_f32_e32 v146, v152, v146
	v_exp_f32_e32 v156, v156
	v_sub_f32_e32 v157, v157, v213
	v_add_f32_e32 v146, v153, v146
	v_exp_f32_e32 v157, v157
	v_sub_f32_e32 v158, v158, v213
	v_add_f32_e32 v146, v154, v146
	v_exp_f32_e32 v158, v158
	v_sub_f32_e32 v159, v159, v213
	v_add_f32_e32 v146, v155, v146
	v_exp_f32_e32 v159, v159
	v_sub_f32_e32 v160, v160, v213
	v_add_f32_e32 v146, v156, v146
	v_exp_f32_e32 v160, v160
	v_sub_f32_e32 v161, v161, v213
	v_add_f32_e32 v146, v157, v146
	v_exp_f32_e32 v161, v161
	v_sub_f32_e32 v130, v130, v213
	v_add_f32_e32 v146, v158, v146
	v_exp_f32_e32 v130, v130
	v_sub_f32_e32 v131, v131, v213
	v_add_f32_e32 v146, v159, v146
	v_exp_f32_e32 v131, v131
	v_sub_f32_e32 v132, v132, v213
	v_add_f32_e32 v146, v160, v146
	v_exp_f32_e32 v132, v132
	v_sub_f32_e32 v133, v133, v213
	v_add_f32_e32 v146, v161, v146
	v_exp_f32_e32 v133, v133
	v_sub_f32_e32 v134, v134, v213
	v_add_f32_e32 v146, v130, v146
	v_exp_f32_e32 v214, v134
	v_sub_f32_e32 v135, v135, v213
	v_add_f32_e32 v146, v131, v146
	v_exp_f32_e32 v215, v135
	v_sub_f32_e32 v135, v136, v213
	v_add_f32_e32 v146, v132, v146
	v_exp_f32_e32 v216, v135
	v_sub_f32_e32 v135, v137, v213
	v_add_f32_e32 v146, v133, v146
	v_exp_f32_e32 v137, v135
	v_sub_f32_e32 v135, v138, v213
	v_add_f32_e32 v134, v214, v146
	v_exp_f32_e32 v217, v135
	v_sub_f32_e32 v135, v139, v213
	v_add_f32_e32 v134, v215, v134
	v_exp_f32_e32 v218, v135
	v_sub_f32_e32 v135, v140, v213
	v_add_f32_e32 v134, v216, v134
	v_exp_f32_e32 v219, v135
	v_sub_f32_e32 v135, v141, v213
	v_add_f32_e32 v134, v137, v134
	v_exp_f32_e32 v220, v135
	v_sub_f32_e32 v135, v142, v213
	v_add_f32_e32 v134, v217, v134
	v_exp_f32_e32 v221, v135
	v_sub_f32_e32 v135, v143, v213
	v_add_f32_e32 v134, v218, v134
	v_exp_f32_e32 v222, v135
	v_sub_f32_e32 v135, v144, v213
	v_add_f32_e32 v134, v219, v134
	v_exp_f32_e32 v223, v135
	v_sub_f32_e32 v135, v145, v213
	v_add_f32_e32 v134, v220, v134
	v_exp_f32_e32 v213, v135
	v_add_f32_e32 v134, v221, v134
	v_add_f32_e32 v134, v222, v134
	s_and_b64 s[4:5], s[14:15], exec
	v_add_f32_e32 v134, v223, v134
	s_movk_i32 s4, 0x4800
	v_add_f32_e32 v146, v213, v134
	s_cselect_b32 s4, s4, 0x9000
	v_fmac_f32_e32 v146, v197, v128
	v_add_u32_e32 v128, s4, v208
	v_cvt_pk_bf16_f32 v143, v148, v149
	v_cvt_pk_bf16_f32 v144, v150, v151
	v_cvt_pk_bf16_f32 v145, v152, v153
	v_cvt_pk_bf16_f32 v138, v154, v155
	ds_read_b128 v[148:151], v128
	ds_read_b128 v[152:155], v128 offset:32
	v_cvt_pk_bf16_f32 v142, v212, v147
	v_cvt_pk_bf16_f32 v139, v156, v157
	v_cvt_pk_bf16_f32 v140, v158, v159
	s_waitcnt lgkmcnt(1)
	v_mfma_f32_32x32x16_bf16 v[112:127], v[148:151], v[142:145], v[112:127]
	v_cvt_pk_bf16_f32 v141, v160, v161
	ds_read_b128 v[148:151], v128 offset:64
	v_cvt_pk_bf16_f32 v134, v130, v131
	v_cvt_pk_bf16_f32 v135, v132, v133
	v_cvt_pk_bf16_f32 v136, v214, v215
	v_cvt_pk_bf16_f32 v137, v216, v137
	v_cvt_pk_bf16_f32 v130, v217, v218
	s_waitcnt lgkmcnt(1)
	v_mfma_f32_32x32x16_bf16 v[112:127], v[152:155], v[138:141], v[112:127]
	v_cvt_pk_bf16_f32 v131, v219, v220
	v_cvt_pk_bf16_f32 v132, v221, v222
	v_cvt_pk_bf16_f32 v133, v223, v213
	v_mov_b32_e32 v197, v146
	s_waitcnt lgkmcnt(0)
	v_mfma_f32_32x32x16_bf16 v[112:127], v[148:151], v[134:137], v[112:127]
	ds_read_b128 v[148:151], v128 offset:96
	ds_read_b128 v[152:155], v128 offset:4608
	ds_read_b128 v[156:159], v128 offset:4640
	ds_read_b128 v[212:215], v128 offset:4672
	s_waitcnt lgkmcnt(3)
	v_mfma_f32_32x32x16_bf16 v[112:127], v[148:151], v[130:133], v[112:127]
	ds_read_b128 v[148:151], v128 offset:4704
	s_waitcnt lgkmcnt(3)
	v_mfma_f32_32x32x16_bf16 v[96:111], v[152:155], v[142:145], v[96:111]
	ds_read_b128 v[152:155], v128 offset:9216
	s_waitcnt lgkmcnt(3)
	v_mfma_f32_32x32x16_bf16 v[96:111], v[156:159], v[138:141], v[96:111]
	ds_read_b128 v[156:159], v128 offset:9248
	s_waitcnt lgkmcnt(3)
	v_mfma_f32_32x32x16_bf16 v[96:111], v[212:215], v[134:137], v[96:111]
	ds_read_b128 v[212:215], v128 offset:9280
	s_waitcnt lgkmcnt(3)
	v_mfma_f32_32x32x16_bf16 v[96:111], v[148:151], v[130:133], v[96:111]
	ds_read_b128 v[148:151], v128 offset:9312
	s_waitcnt lgkmcnt(3)
	v_mfma_f32_32x32x16_bf16 v[80:95], v[152:155], v[142:145], v[80:95]
	ds_read_b128 v[152:155], v128 offset:13824
	s_waitcnt lgkmcnt(3)
	v_mfma_f32_32x32x16_bf16 v[80:95], v[156:159], v[138:141], v[80:95]
	ds_read_b128 v[156:159], v128 offset:13856
	s_waitcnt lgkmcnt(3)
	v_mfma_f32_32x32x16_bf16 v[80:95], v[212:215], v[134:137], v[80:95]
	ds_read_b128 v[212:215], v128 offset:13888
	s_waitcnt lgkmcnt(3)
	v_mfma_f32_32x32x16_bf16 v[80:95], v[148:151], v[130:133], v[80:95]
	ds_read_b128 v[148:151], v128 offset:13920
	s_waitcnt lgkmcnt(3)
	v_mfma_f32_32x32x16_bf16 v[64:79], v[152:155], v[142:145], v[64:79]
	s_waitcnt lgkmcnt(2)
	v_mfma_f32_32x32x16_bf16 v[64:79], v[156:159], v[138:141], v[64:79]
	s_waitcnt lgkmcnt(1)
	v_mfma_f32_32x32x16_bf16 v[64:79], v[212:215], v[134:137], v[64:79]
	s_waitcnt lgkmcnt(0)
	v_mfma_f32_32x32x16_bf16 v[64:79], v[148:151], v[130:133], v[64:79]
	s_andn2_b64 vcc, exec, s[36:37]
	s_cbranch_vccz .LBB0_353
	s_branch .LBB0_354

.LBB0_371:
	v_readlane_b32 s4, v255, 11
	v_readlane_b32 s5, v255, 12
	s_add_u32 s4, s4, s10
	s_addc_u32 s5, s5, s9
	s_lshl_b32 s6, s29, 7
	s_add_u32 s8, s4, s6
	s_addc_u32 s9, s5, 0
	s_add_u32 s96, s8, 0x400
	v_pk_add_f32 v[2:3], v[2:3], v[4:5] op_sel_hi:[1,0]
	v_pk_add_f32 v[0:1], v[0:1], v[4:5] op_sel_hi:[1,0]
	v_lshl_add_u32 v4, v246, 4, 0
	s_addc_u32 s97, s9, 0
	v_mov_b32_e32 v8, v241
	ds_write_b128 v4, v[0:3] offset:55296
	s_waitcnt lgkmcnt(0)
	s_barrier
	s_add_u32 s36, s8, 0x800
	s_addc_u32 s37, s9, 0
	v_readfirstlane_b32 s5, v8
	s_ashr_i32 s4, s5, 6
	s_lshl_b32 s30, s28, 8
	s_lshl_b32 s6, s4, 5
	v_and_b32_e32 v34, 31, v8
	s_add_i32 s31, s6, s30
	v_bfe_u32 v35, v8, 5, 1
	v_or_b32_e32 v10, s31, v34
	v_mov_b64_e32 v[0:1], s[8:9]
	s_movk_i32 s7, 0x3000
	v_mad_i64_i32 v[0:1], s[8:9], v10, s7, v[0:1]
	v_lshlrev_b32_e32 v128, 4, v35
	v_lshl_add_u64 v[0:1], v[0:1], 0, v[128:129]
	global_load_dwordx4 v[2:5], v[0:1], off
	global_load_dwordx4 v[16:19], v[0:1], off offset:32
	global_load_dwordx4 v[20:23], v[0:1], off offset:64
	global_load_dwordx4 v[24:27], v[0:1], off offset:96
	s_mov_b32 s8, 0x3e38aa3b
	v_and_b32_e32 v33, 63, v8
	s_ashr_i32 s21, s5, 7
	s_movk_i32 s5, 0x90
	s_lshl_b32 s24, s28, 2
	s_mul_i32 s19, s28, 0x300000
	v_mov_b32_e32 v249, v241
	v_mul_u32_u24_e32 v243, 0x90, v34
	s_waitcnt vmcnt(3)
	v_and_b32_e32 v7, 0xffff0000, v2
	v_lshlrev_b32_e32 v6, 16, v2
	v_pk_mul_f32 v[6:7], v[6:7], s[8:9] op_sel_hi:[1,0]
	s_nop 0
	v_cvt_pk_bf16_f32 v192, v6, v7
	v_and_b32_e32 v7, 0xffff0000, v3
	v_lshlrev_b32_e32 v6, 16, v3
	v_pk_mul_f32 v[2:3], v[6:7], s[8:9] op_sel_hi:[1,0]
	s_nop 0
	v_cvt_pk_bf16_f32 v193, v2, v3
	v_and_b32_e32 v3, 0xffff0000, v4
	v_lshlrev_b32_e32 v2, 16, v4
	v_pk_mul_f32 v[2:3], v[2:3], s[8:9] op_sel_hi:[1,0]
	s_nop 0
	v_cvt_pk_bf16_f32 v194, v2, v3
	v_and_b32_e32 v3, 0xffff0000, v5
	v_lshlrev_b32_e32 v2, 16, v5
	v_pk_mul_f32 v[2:3], v[2:3], s[8:9] op_sel_hi:[1,0]
	s_nop 0
	v_cvt_pk_bf16_f32 v195, v2, v3
	s_waitcnt vmcnt(2)
	v_and_b32_e32 v7, 0xffff0000, v16
	v_lshlrev_b32_e32 v6, 16, v16
	v_pk_mul_f32 v[6:7], v[6:7], s[8:9] op_sel_hi:[1,0]
	s_nop 0
	v_cvt_pk_bf16_f32 v196, v6, v7
	v_and_b32_e32 v7, 0xffff0000, v17
	v_lshlrev_b32_e32 v6, 16, v17
	v_pk_mul_f32 v[2:3], v[6:7], s[8:9] op_sel_hi:[1,0]
	s_nop 0
	v_cvt_pk_bf16_f32 v197, v2, v3
	v_and_b32_e32 v3, 0xffff0000, v18
	v_lshlrev_b32_e32 v2, 16, v18
	v_pk_mul_f32 v[2:3], v[2:3], s[8:9] op_sel_hi:[1,0]
	s_nop 0
	v_cvt_pk_bf16_f32 v198, v2, v3
	v_and_b32_e32 v3, 0xffff0000, v19
	v_lshlrev_b32_e32 v2, 16, v19
	v_pk_mul_f32 v[2:3], v[2:3], s[8:9] op_sel_hi:[1,0]
	s_nop 0
	v_cvt_pk_bf16_f32 v199, v2, v3
	s_waitcnt vmcnt(1)
	v_and_b32_e32 v7, 0xffff0000, v20
	v_lshlrev_b32_e32 v6, 16, v20
	v_pk_mul_f32 v[6:7], v[6:7], s[8:9] op_sel_hi:[1,0]
	s_nop 0
	v_cvt_pk_bf16_f32 v200, v6, v7
	v_and_b32_e32 v7, 0xffff0000, v21
	v_lshlrev_b32_e32 v6, 16, v21
	v_pk_mul_f32 v[2:3], v[6:7], s[8:9] op_sel_hi:[1,0]
	s_nop 0
	v_cvt_pk_bf16_f32 v201, v2, v3
	v_and_b32_e32 v3, 0xffff0000, v22
	v_lshlrev_b32_e32 v2, 16, v22
	v_pk_mul_f32 v[2:3], v[2:3], s[8:9] op_sel_hi:[1,0]
	s_nop 0
	v_cvt_pk_bf16_f32 v202, v2, v3
	v_and_b32_e32 v3, 0xffff0000, v23
	v_lshlrev_b32_e32 v2, 16, v23
	v_pk_mul_f32 v[2:3], v[2:3], s[8:9] op_sel_hi:[1,0]
	s_nop 0
	v_cvt_pk_bf16_f32 v203, v2, v3
	s_waitcnt vmcnt(0)
	v_and_b32_e32 v5, 0xffff0000, v24
	v_lshlrev_b32_e32 v4, 16, v24
	v_pk_mul_f32 v[4:5], v[4:5], s[8:9] op_sel_hi:[1,0]
	s_nop 0
	v_cvt_pk_bf16_f32 v204, v4, v5
	v_and_b32_e32 v5, 0xffff0000, v25
	v_lshlrev_b32_e32 v4, 16, v25
	v_pk_mul_f32 v[0:1], v[4:5], s[8:9] op_sel_hi:[1,0]
	s_nop 0
	v_cvt_pk_bf16_f32 v205, v0, v1
	v_and_b32_e32 v1, 0xffff0000, v26
	v_lshlrev_b32_e32 v0, 16, v26
	v_pk_mul_f32 v[0:1], v[0:1], s[8:9] op_sel_hi:[1,0]
	v_lshlrev_b32_e32 v2, 1, v8
	v_cvt_pk_bf16_f32 v206, v0, v1
	v_and_b32_e32 v1, 0xffff0000, v27
	v_lshlrev_b32_e32 v0, 16, v27
	v_pk_mul_f32 v[0:1], v[0:1], s[8:9] op_sel_hi:[1,0]
	s_nop 0
	v_cvt_pk_bf16_f32 v207, v0, v1
	v_lshlrev_b32_e32 v1, 4, v8
	v_and_b32_e32 v32, 0x70, v1
	v_mul_u32_u24_e32 v1, 0x3000, v33
	v_lshl_add_u32 v240, s4, 4, v1
	v_and_b32_e32 v1, 51, v8
	v_ashrrev_i32_e32 v0, 3, v8
	v_and_or_b32 v1, v2, 8, v1
	v_lshlrev_b32_e32 v1, 1, v1
	v_and_b32_e32 v2, 8, v8
	v_mad_u64_u32 v[8:9], s[8:9], v0, s5, v[32:33]
	s_mulk_i32 s4, 0x480
	v_mul_lo_u32 v36, v0, s7
	v_or3_b32 v9, v1, v2, s4
	s_or_b32 s4, s24, 3
	v_or_b32_e32 v11, v32, v36
	v_lshl_add_u32 v0, v10, 2, 0
	s_mul_i32 s5, s4, 0xc0000
	ds_read_b32 v144, v0 offset:55296
	v_add_u32_e32 v0, s5, v11
	global_load_dwordx4 v[4:7], v0, s[96:97]
	v_add_u32_e32 v10, s5, v240
	s_add_i32 s5, s19, 0x180000
	v_add_u32_e32 v0, s5, v11
	v_add_u32_e32 v11, s19, v11
	v_add_u32_e32 v11, 0xc0000, v11
	global_load_dwordx4 v[208:211], v11, s[96:97]
	v_add_u32_e32 v11, s5, v240
	v_add_u32_e32 v241, 0, v8
	global_load_dwordx4 v[0:3], v0, s[96:97]
	v_add_u32_e32 v242, 0, v9
	global_load_dwordx4 v[212:215], v11, s[36:37]
	s_cmp_gt_i32 s21, 2
	s_waitcnt vmcnt(3)
	ds_write_b128 v241, v[4:7]
	global_load_dwordx4 v[4:7], v10, s[36:37]
	s_waitcnt vmcnt(0)
	ds_write_b16 v242, v4 offset:18432
	ds_write_b16_d16_hi v242, v4 offset:18576
	ds_write_b16 v242, v5 offset:18720
	ds_write_b16_d16_hi v242, v5 offset:18864
	ds_write_b16 v242, v6 offset:19008
	ds_write_b16_d16_hi v242, v6 offset:19152
	ds_write_b16 v242, v7 offset:19296
	ds_write_b16_d16_hi v242, v7 offset:19440
	ds_write_b128 v241, v[0:3] offset:9216
	s_waitcnt lgkmcnt(0)
	s_barrier
	s_cbranch_scc0 .LBB0_379
	s_lshl_b32 s4, s4, 8
	s_add_i32 s4, s4, 0
	v_add_u32_e32 v24, s4, v128
	ds_read_b128 v[0:3], v24 offset:55392
	ds_read_b128 v[16:19], v24 offset:55296
	ds_read_b128 v[4:7], v24 offset:55328
	ds_read_b128 v[8:11], v24 offset:55360
	v_add3_u32 v37, v128, v243, 0
	s_waitcnt lgkmcnt(3)
	v_sub_f32_e32 v15, v144, v3
	v_sub_f32_e32 v14, v144, v2
	v_sub_f32_e32 v13, v144, v1
	v_sub_f32_e32 v12, v144, v0
	s_waitcnt lgkmcnt(0)
	v_sub_f32_e32 v11, v144, v11
	v_sub_f32_e32 v10, v144, v10
	v_sub_f32_e32 v9, v144, v9
	v_sub_f32_e32 v8, v144, v8
	v_sub_f32_e32 v7, v144, v7
	v_sub_f32_e32 v6, v144, v6
	v_sub_f32_e32 v5, v144, v5
	v_sub_f32_e32 v4, v144, v4
	v_sub_f32_e32 v3, v144, v19
	v_sub_f32_e32 v2, v144, v18
	v_sub_f32_e32 v1, v144, v17
	v_sub_f32_e32 v0, v144, v16
	ds_read_b128 v[16:19], v24 offset:55520
	ds_read_b128 v[38:41], v24 offset:55424
	ds_read_b128 v[20:23], v24 offset:55456
	ds_read_b128 v[24:27], v24 offset:55488
	s_waitcnt lgkmcnt(3)
	v_sub_f32_e32 v31, v144, v19
	v_sub_f32_e32 v30, v144, v18
	v_sub_f32_e32 v29, v144, v17
	v_sub_f32_e32 v28, v144, v16
	s_waitcnt lgkmcnt(0)
	v_sub_f32_e32 v27, v144, v27
	v_sub_f32_e32 v26, v144, v26
	v_sub_f32_e32 v25, v144, v25
	v_sub_f32_e32 v24, v144, v24
	v_sub_f32_e32 v23, v144, v23
	v_sub_f32_e32 v22, v144, v22
	v_sub_f32_e32 v21, v144, v21
	v_sub_f32_e32 v20, v144, v20
	v_sub_f32_e32 v19, v144, v41
	v_sub_f32_e32 v18, v144, v40
	v_sub_f32_e32 v17, v144, v39
	v_sub_f32_e32 v16, v144, v38
	ds_read_b128 v[38:41], v37
	ds_read_b128 v[44:47], v37 offset:4608
	ds_read_b128 v[48:51], v37 offset:32
	ds_read_b128 v[52:55], v37 offset:4640
	s_waitcnt lgkmcnt(3)
	v_mfma_f32_32x32x16_bf16 v[0:15], v[38:41], v[192:195], v[0:15]
	ds_read_b128 v[38:41], v37 offset:64
	s_waitcnt lgkmcnt(3)
	v_mfma_f32_32x32x16_bf16 v[16:31], v[44:47], v[192:195], v[16:31]
	ds_read_b128 v[44:47], v37 offset:4672
	s_waitcnt lgkmcnt(3)
	v_mfma_f32_32x32x16_bf16 v[0:15], v[48:51], v[196:199], v[0:15]
	ds_read_b128 v[48:51], v37 offset:96
	s_waitcnt lgkmcnt(3)
	v_mfma_f32_32x32x16_bf16 v[16:31], v[52:55], v[196:199], v[16:31]
	ds_read_b128 v[52:55], v37 offset:4704
	s_waitcnt lgkmcnt(3)
	v_mfma_f32_32x32x16_bf16 v[0:15], v[38:41], v[200:203], v[0:15]
	s_waitcnt lgkmcnt(2)
	v_mfma_f32_32x32x16_bf16 v[16:31], v[44:47], v[200:203], v[16:31]
	s_waitcnt lgkmcnt(1)
	v_mfma_f32_32x32x16_bf16 v[0:15], v[48:51], v[204:207], v[0:15]
	s_waitcnt lgkmcnt(0)
	v_mfma_f32_32x32x16_bf16 v[16:31], v[52:55], v[204:207], v[16:31]
	s_cbranch_execz .LBB0_380
	s_branch .LBB0_381

.LBB0_387:
	s_add_i32 s4, s20, -5
	s_cmp_lt_u32 s4, s18
	s_cselect_b64 s[16:17], -1, 0
	s_cmp_ge_u32 s4, s18
	s_cbranch_scc1 .LBB0_390
	s_add_i32 s4, s23, 3
	s_cmp_gt_i32 s4, s21
	s_cbranch_scc1 .LBB0_390
	ds_read_b128 v[172:175], v244 offset:864
	ds_read_b128 v[168:171], v244 offset:832
	ds_read_b128 v[164:167], v244 offset:800
	ds_read_b128 v[160:163], v244 offset:768
	ds_read_b128 v[188:191], v244 offset:992
	ds_read_b128 v[184:187], v244 offset:960
	ds_read_b128 v[180:183], v244 offset:928
	ds_read_b128 v[176:179], v244 offset:896
	v_add_u32_e32 v68, v247, v243
	s_waitcnt lgkmcnt(7)
	v_sub_f32_e32 v175, v159, v175
	v_sub_f32_e32 v174, v158, v174
	v_sub_f32_e32 v173, v157, v173
	v_sub_f32_e32 v172, v156, v172
	s_waitcnt lgkmcnt(6)
	v_sub_f32_e32 v171, v155, v171
	v_sub_f32_e32 v170, v154, v170
	v_sub_f32_e32 v169, v153, v169
	v_sub_f32_e32 v168, v152, v168
	s_waitcnt lgkmcnt(5)
	v_sub_f32_e32 v167, v151, v167
	v_sub_f32_e32 v166, v150, v166
	v_sub_f32_e32 v165, v149, v165
	v_sub_f32_e32 v164, v148, v164
	s_waitcnt lgkmcnt(4)
	v_sub_f32_e32 v163, v147, v163
	v_sub_f32_e32 v162, v146, v162
	v_sub_f32_e32 v161, v145, v161
	v_sub_f32_e32 v160, v144, v160
	s_waitcnt lgkmcnt(3)
	v_sub_f32_e32 v191, v159, v191
	v_sub_f32_e32 v190, v158, v190
	v_sub_f32_e32 v189, v157, v189
	v_sub_f32_e32 v188, v156, v188
	s_waitcnt lgkmcnt(2)
	v_sub_f32_e32 v187, v155, v187
	v_sub_f32_e32 v186, v154, v186
	v_sub_f32_e32 v185, v153, v185
	v_sub_f32_e32 v184, v152, v184
	s_waitcnt lgkmcnt(1)
	v_sub_f32_e32 v183, v151, v183
	v_sub_f32_e32 v182, v150, v182
	v_sub_f32_e32 v181, v149, v181
	v_sub_f32_e32 v180, v148, v180
	s_waitcnt lgkmcnt(0)
	v_sub_f32_e32 v179, v147, v179
	v_sub_f32_e32 v178, v146, v178
	v_sub_f32_e32 v177, v145, v177
	v_sub_f32_e32 v176, v144, v176
	ds_read_b128 v[64:67], v68 offset:9216
	ds_read_b128 v[72:75], v68 offset:13824
	ds_read_b128 v[76:79], v68 offset:9248
	ds_read_b128 v[80:83], v68 offset:13856
	s_waitcnt lgkmcnt(3)
	v_mfma_f32_32x32x16_bf16 v[160:175], v[64:67], v[192:195], v[160:175]
	ds_read_b128 v[64:67], v68 offset:9280
	s_waitcnt lgkmcnt(3)
	v_mfma_f32_32x32x16_bf16 v[176:191], v[72:75], v[192:195], v[176:191]
	ds_read_b128 v[72:75], v68 offset:13888
	s_waitcnt lgkmcnt(3)
	v_mfma_f32_32x32x16_bf16 v[160:175], v[76:79], v[196:199], v[160:175]
	ds_read_b128 v[76:79], v68 offset:9312
	s_waitcnt lgkmcnt(3)
	v_mfma_f32_32x32x16_bf16 v[176:191], v[80:83], v[196:199], v[176:191]
	ds_read_b128 v[80:83], v68 offset:13920
	s_waitcnt lgkmcnt(3)
	v_mfma_f32_32x32x16_bf16 v[160:175], v[64:67], v[200:203], v[160:175]
	s_waitcnt lgkmcnt(2)
	v_mfma_f32_32x32x16_bf16 v[176:191], v[72:75], v[200:203], v[176:191]
	s_waitcnt lgkmcnt(1)
	v_mfma_f32_32x32x16_bf16 v[160:175], v[76:79], v[204:207], v[160:175]
	s_waitcnt lgkmcnt(0)
	v_mfma_f32_32x32x16_bf16 v[176:191], v[80:83], v[204:207], v[176:191]

.LBB0_408:
	s_add_i32 s4, s23, 2
	s_cmp_gt_i32 s4, s21
	s_cbranch_scc1 .LBB0_410
	ds_read_b128 v[12:15], v244 offset:608
	ds_read_b128 v[8:11], v244 offset:576
	ds_read_b128 v[4:7], v244 offset:544
	ds_read_b128 v[0:3], v244 offset:512
	ds_read_b128 v[28:31], v244 offset:736
	ds_read_b128 v[24:27], v244 offset:704
	ds_read_b128 v[20:23], v244 offset:672
	ds_read_b128 v[16:19], v244 offset:640
	v_add_u32_e32 v97, v247, v243
	s_waitcnt lgkmcnt(7)
	v_sub_f32_e32 v15, v159, v15
	v_sub_f32_e32 v14, v158, v14
	v_sub_f32_e32 v13, v157, v13
	v_sub_f32_e32 v12, v156, v12
	s_waitcnt lgkmcnt(6)
	v_sub_f32_e32 v11, v155, v11
	v_sub_f32_e32 v10, v154, v10
	v_sub_f32_e32 v9, v153, v9
	v_sub_f32_e32 v8, v152, v8
	s_waitcnt lgkmcnt(5)
	v_sub_f32_e32 v7, v151, v7
	v_sub_f32_e32 v6, v150, v6
	v_sub_f32_e32 v5, v149, v5
	v_sub_f32_e32 v4, v148, v4
	s_waitcnt lgkmcnt(4)
	v_sub_f32_e32 v3, v147, v3
	v_sub_f32_e32 v2, v146, v2
	v_sub_f32_e32 v1, v145, v1
	v_sub_f32_e32 v0, v144, v0
	s_waitcnt lgkmcnt(3)
	v_sub_f32_e32 v31, v159, v31
	v_sub_f32_e32 v30, v158, v30
	v_sub_f32_e32 v29, v157, v29
	v_sub_f32_e32 v28, v156, v28
	s_waitcnt lgkmcnt(2)
	v_sub_f32_e32 v27, v155, v27
	v_sub_f32_e32 v26, v154, v26
	v_sub_f32_e32 v25, v153, v25
	v_sub_f32_e32 v24, v152, v24
	s_waitcnt lgkmcnt(1)
	v_sub_f32_e32 v23, v151, v23
	v_sub_f32_e32 v22, v150, v22
	v_sub_f32_e32 v21, v149, v21
	v_sub_f32_e32 v20, v148, v20
	s_waitcnt lgkmcnt(0)
	v_sub_f32_e32 v19, v147, v19
	v_sub_f32_e32 v18, v146, v18
	v_sub_f32_e32 v17, v145, v17
	v_sub_f32_e32 v16, v144, v16
	ds_read_b128 v[98:101], v97
	ds_read_b128 v[136:139], v97 offset:4608
	ds_read_b128 v[140:143], v97 offset:32
	s_waitcnt lgkmcnt(2)
	v_mfma_f32_32x32x16_bf16 v[0:15], v[98:101], v[192:195], v[0:15]
	ds_read_b128 v[98:101], v97 offset:4640
	s_waitcnt lgkmcnt(2)
	v_mfma_f32_32x32x16_bf16 v[16:31], v[136:139], v[192:195], v[16:31]
	ds_read_b128 v[136:139], v97 offset:64
	s_waitcnt lgkmcnt(2)
	v_mfma_f32_32x32x16_bf16 v[0:15], v[140:143], v[196:199], v[0:15]
	ds_read_b128 v[140:143], v97 offset:4672
	s_waitcnt lgkmcnt(2)
	v_mfma_f32_32x32x16_bf16 v[16:31], v[98:101], v[196:199], v[16:31]
	ds_read_b128 v[98:101], v97 offset:96
	s_waitcnt lgkmcnt(2)
	v_mfma_f32_32x32x16_bf16 v[0:15], v[136:139], v[200:203], v[0:15]
	ds_read_b128 v[136:139], v97 offset:4704
	s_waitcnt lgkmcnt(2)
	v_mfma_f32_32x32x16_bf16 v[16:31], v[140:143], v[200:203], v[16:31]
	s_waitcnt lgkmcnt(1)
	v_mfma_f32_32x32x16_bf16 v[0:15], v[98:101], v[204:207], v[0:15]
	s_waitcnt lgkmcnt(0)
	v_mfma_f32_32x32x16_bf16 v[16:31], v[136:139], v[204:207], v[16:31]

.LBB0_427:
	s_add_i32 s4, s23, 1
	s_cmp_gt_i32 s4, s21
	s_cbranch_scc1 .LBB0_429
	ds_read_b128 v[172:175], v244 offset:352
	ds_read_b128 v[168:171], v244 offset:320
	ds_read_b128 v[164:167], v244 offset:288
	ds_read_b128 v[160:163], v244 offset:256
	ds_read_b128 v[188:191], v244 offset:480
	ds_read_b128 v[184:187], v244 offset:448
	ds_read_b128 v[180:183], v244 offset:416
	ds_read_b128 v[176:179], v244 offset:384
	v_add_u32_e32 v96, v247, v243
	s_waitcnt lgkmcnt(7)
	v_sub_f32_e32 v175, v159, v175
	v_sub_f32_e32 v174, v158, v174
	v_sub_f32_e32 v173, v157, v173
	v_sub_f32_e32 v172, v156, v172
	s_waitcnt lgkmcnt(6)
	v_sub_f32_e32 v171, v155, v171
	v_sub_f32_e32 v170, v154, v170
	v_sub_f32_e32 v169, v153, v169
	v_sub_f32_e32 v168, v152, v168
	s_waitcnt lgkmcnt(5)
	v_sub_f32_e32 v167, v151, v167
	v_sub_f32_e32 v166, v150, v166
	v_sub_f32_e32 v165, v149, v165
	v_sub_f32_e32 v164, v148, v164
	s_waitcnt lgkmcnt(4)
	v_sub_f32_e32 v163, v147, v163
	v_sub_f32_e32 v162, v146, v162
	v_sub_f32_e32 v161, v145, v161
	v_sub_f32_e32 v160, v144, v160
	s_waitcnt lgkmcnt(3)
	v_sub_f32_e32 v191, v159, v191
	v_sub_f32_e32 v190, v158, v190
	v_sub_f32_e32 v189, v157, v189
	v_sub_f32_e32 v188, v156, v188
	s_waitcnt lgkmcnt(2)
	v_sub_f32_e32 v187, v155, v187
	v_sub_f32_e32 v186, v154, v186
	v_sub_f32_e32 v185, v153, v185
	v_sub_f32_e32 v184, v152, v184
	s_waitcnt lgkmcnt(1)
	v_sub_f32_e32 v183, v151, v183
	v_sub_f32_e32 v182, v150, v182
	v_sub_f32_e32 v181, v149, v181
	v_sub_f32_e32 v180, v148, v180
	s_waitcnt lgkmcnt(0)
	v_sub_f32_e32 v179, v147, v179
	v_sub_f32_e32 v178, v146, v178
	v_sub_f32_e32 v177, v145, v177
	v_sub_f32_e32 v176, v144, v176
	ds_read_b128 v[98:101], v96 offset:9216
	ds_read_b128 v[136:139], v96 offset:13824
	ds_read_b128 v[140:143], v96 offset:9248
	s_waitcnt lgkmcnt(2)
	v_mfma_f32_32x32x16_bf16 v[160:175], v[98:101], v[192:195], v[160:175]
	ds_read_b128 v[98:101], v96 offset:13856
	s_waitcnt lgkmcnt(2)
	v_mfma_f32_32x32x16_bf16 v[176:191], v[136:139], v[192:195], v[176:191]
	ds_read_b128 v[136:139], v96 offset:9280
	s_waitcnt lgkmcnt(2)
	v_mfma_f32_32x32x16_bf16 v[160:175], v[140:143], v[196:199], v[160:175]
	ds_read_b128 v[140:143], v96 offset:13888
	s_waitcnt lgkmcnt(2)
	v_mfma_f32_32x32x16_bf16 v[176:191], v[98:101], v[196:199], v[176:191]
	ds_read_b128 v[98:101], v96 offset:9312
	s_waitcnt lgkmcnt(2)
	v_mfma_f32_32x32x16_bf16 v[160:175], v[136:139], v[200:203], v[160:175]
	ds_read_b128 v[136:139], v96 offset:13920
	s_waitcnt lgkmcnt(2)
	v_mfma_f32_32x32x16_bf16 v[176:191], v[140:143], v[200:203], v[176:191]
	s_waitcnt lgkmcnt(1)
	v_mfma_f32_32x32x16_bf16 v[160:175], v[98:101], v[204:207], v[160:175]
	s_waitcnt lgkmcnt(0)
	v_mfma_f32_32x32x16_bf16 v[176:191], v[136:139], v[204:207], v[176:191]

.LBB0_446:
	s_cmp_gt_i32 s23, s21
	s_cbranch_scc1 .LBB0_448
	ds_read_b128 v[12:15], v244 offset:96
	ds_read_b128 v[8:11], v244 offset:64
	ds_read_b128 v[4:7], v244 offset:32
	ds_read_b128 v[0:3], v244
	ds_read_b128 v[28:31], v244 offset:224
	ds_read_b128 v[24:27], v244 offset:192
	ds_read_b128 v[20:23], v244 offset:160
	ds_read_b128 v[16:19], v244 offset:128
	v_add_u32_e32 v100, v247, v243
	s_waitcnt lgkmcnt(7)
	v_sub_f32_e32 v15, v159, v15
	v_sub_f32_e32 v14, v158, v14
	v_sub_f32_e32 v13, v157, v13
	v_sub_f32_e32 v12, v156, v12
	s_waitcnt lgkmcnt(6)
	v_sub_f32_e32 v11, v155, v11
	v_sub_f32_e32 v10, v154, v10
	v_sub_f32_e32 v9, v153, v9
	v_sub_f32_e32 v8, v152, v8
	s_waitcnt lgkmcnt(5)
	v_sub_f32_e32 v7, v151, v7
	v_sub_f32_e32 v6, v150, v6
	v_sub_f32_e32 v5, v149, v5
	v_sub_f32_e32 v4, v148, v4
	s_waitcnt lgkmcnt(4)
	v_sub_f32_e32 v3, v147, v3
	v_sub_f32_e32 v2, v146, v2
	v_sub_f32_e32 v1, v145, v1
	v_sub_f32_e32 v0, v144, v0
	s_waitcnt lgkmcnt(3)
	v_sub_f32_e32 v31, v159, v31
	v_sub_f32_e32 v30, v158, v30
	v_sub_f32_e32 v29, v157, v29
	v_sub_f32_e32 v28, v156, v28
	s_waitcnt lgkmcnt(2)
	v_sub_f32_e32 v27, v155, v27
	v_sub_f32_e32 v26, v154, v26
	v_sub_f32_e32 v25, v153, v25
	v_sub_f32_e32 v24, v152, v24
	s_waitcnt lgkmcnt(1)
	v_sub_f32_e32 v23, v151, v23
	v_sub_f32_e32 v22, v150, v22
	v_sub_f32_e32 v21, v149, v21
	v_sub_f32_e32 v20, v148, v20
	s_waitcnt lgkmcnt(0)
	v_sub_f32_e32 v19, v147, v19
	v_sub_f32_e32 v18, v146, v18
	v_sub_f32_e32 v17, v145, v17
	v_sub_f32_e32 v16, v144, v16
	ds_read_b128 v[96:99], v100
	ds_read_b128 v[136:139], v100 offset:4608
	ds_read_b128 v[140:143], v100 offset:32
	s_waitcnt lgkmcnt(2)
	v_mfma_f32_32x32x16_bf16 v[0:15], v[96:99], v[192:195], v[0:15]
	ds_read_b128 v[96:99], v100 offset:4640
	s_waitcnt lgkmcnt(2)
	v_mfma_f32_32x32x16_bf16 v[16:31], v[136:139], v[192:195], v[16:31]
	ds_read_b128 v[136:139], v100 offset:64
	s_waitcnt lgkmcnt(2)
	v_mfma_f32_32x32x16_bf16 v[0:15], v[140:143], v[196:199], v[0:15]
	ds_read_b128 v[140:143], v100 offset:4672
	s_waitcnt lgkmcnt(2)
	v_mfma_f32_32x32x16_bf16 v[16:31], v[96:99], v[196:199], v[16:31]
	ds_read_b128 v[96:99], v100 offset:96
	s_waitcnt lgkmcnt(2)
	v_mfma_f32_32x32x16_bf16 v[0:15], v[136:139], v[200:203], v[0:15]
	ds_read_b128 v[136:139], v100 offset:4704
	s_waitcnt lgkmcnt(2)
	v_mfma_f32_32x32x16_bf16 v[16:31], v[140:143], v[200:203], v[16:31]
	s_waitcnt lgkmcnt(1)
	v_mfma_f32_32x32x16_bf16 v[0:15], v[96:99], v[204:207], v[0:15]
	s_waitcnt lgkmcnt(0)
	v_mfma_f32_32x32x16_bf16 v[16:31], v[136:139], v[204:207], v[16:31]
